# full-tile GEMM K-loops: A-fragment ds_reads of load segments 1/4/5 issued inside the preceding MFMA block (MFMA-LDS interleave)
# baseline (speedup 1.0000x reference)
.LBB0_34:
	ds_read_b128 v[164:167], v151
	ds_read_b128 v[168:171], v151 offset:1024
	ds_read_b128 v[172:175], v151 offset:2048
	ds_read_b128 v[176:179], v151 offset:3072
	v_lshl_add_u64 v[204:205], v[138:139], 0, s[12:13]
	v_lshl_add_u64 v[228:229], v[204:205], 0, s[60:61]
	s_add_i32 m0, s1, 0xc000
	ds_read_b128 v[180:183], v0
	ds_read_b128 v[184:187], v0 offset:1024
	ds_read_b128 v[188:191], v0 offset:2048
	ds_read_b128 v[192:195], v0 offset:3072
	ds_read_b128 v[196:199], v0 offset:4096
	ds_read_b128 v[200:203], v0 offset:5120
	ds_read_b128 v[222:225], v0 offset:6144
	ds_read_b128 v[232:235], v0 offset:7168
	global_load_lds_dwordx4 v[228:229], off
	v_lshl_add_u64 v[210:211], v[140:141], 0, s[12:13]
	s_add_i32 m0, s1, 0xe000
	v_lshl_add_u64 v[152:153], v[210:211], 0, s[60:61]
	global_load_lds_dwordx4 v[152:153], off
	s_waitcnt lgkmcnt(8)
	s_barrier
	s_waitcnt lgkmcnt(0)
	v_mfma_f32_16x16x32_bf16 v[126:129], v[164:167], v[180:183], v[126:129]
	v_mfma_f32_16x16x32_bf16 v[122:125], v[172:175], v[180:183], v[122:125]
	v_mfma_f32_16x16x32_bf16 v[118:121], v[164:167], v[188:191], v[118:121]
	ds_read_b128 v[236:239], v151 offset:16384
	v_mfma_f32_16x16x32_bf16 v[114:117], v[172:175], v[188:191], v[114:117]
	v_mfma_f32_16x16x32_bf16 v[110:113], v[164:167], v[196:199], v[110:113]
	v_mfma_f32_16x16x32_bf16 v[106:109], v[172:175], v[196:199], v[106:109]
	ds_read_b128 v[240:243], v151 offset:17408
	v_mfma_f32_16x16x32_bf16 v[102:105], v[164:167], v[222:225], v[102:105]
	v_mfma_f32_16x16x32_bf16 v[98:101], v[172:175], v[222:225], v[98:101]
	v_mfma_f32_16x16x32_bf16 v[126:129], v[168:171], v[184:187], v[126:129]
	ds_read_b128 v[244:247], v151 offset:18432
	v_mfma_f32_16x16x32_bf16 v[122:125], v[176:179], v[184:187], v[122:125]
	v_mfma_f32_16x16x32_bf16 v[118:121], v[168:171], v[192:195], v[118:121]
	v_mfma_f32_16x16x32_bf16 v[114:117], v[176:179], v[192:195], v[114:117]
	ds_read_b128 v[248:251], v151 offset:19456
	v_mfma_f32_16x16x32_bf16 v[110:113], v[168:171], v[200:203], v[110:113]
	v_mfma_f32_16x16x32_bf16 v[106:109], v[176:179], v[200:203], v[106:109]
	v_mfma_f32_16x16x32_bf16 v[102:105], v[168:171], v[232:235], v[102:105]
	v_mfma_f32_16x16x32_bf16 v[98:101], v[176:179], v[232:235], v[98:101]
	s_barrier
	v_lshl_add_u64 v[216:217], v[134:135], 0, s[12:13]
	s_add_i32 m0, s1, 0xff00
	global_load_lds_dwordx4 v[216:217], off offset:256
	s_add_i32 m0, s1, 0x11f00
	v_lshl_add_u64 v[218:219], v[136:137], 0, s[12:13]
	global_load_lds_dwordx4 v[218:219], off offset:256
	s_barrier
	s_waitcnt lgkmcnt(0)
	v_mfma_f32_16x16x32_bf16 v[94:97], v[236:239], v[180:183], v[94:97]
	v_mfma_f32_16x16x32_bf16 v[90:93], v[244:247], v[180:183], v[90:93]
	v_mfma_f32_16x16x32_bf16 v[86:89], v[236:239], v[188:191], v[86:89]
	v_mfma_f32_16x16x32_bf16 v[70:73], v[244:247], v[188:191], v[70:73]
	v_mfma_f32_16x16x32_bf16 v[62:65], v[236:239], v[196:199], v[62:65]
	v_mfma_f32_16x16x32_bf16 v[58:61], v[244:247], v[196:199], v[58:61]
	v_mfma_f32_16x16x32_bf16 v[54:57], v[236:239], v[222:225], v[54:57]
	v_mfma_f32_16x16x32_bf16 v[50:53], v[244:247], v[222:225], v[50:53]
	v_mfma_f32_16x16x32_bf16 v[94:97], v[240:243], v[184:187], v[94:97]
	v_mfma_f32_16x16x32_bf16 v[90:93], v[248:251], v[184:187], v[90:93]
	v_mfma_f32_16x16x32_bf16 v[86:89], v[240:243], v[192:195], v[86:89]
	v_mfma_f32_16x16x32_bf16 v[70:73], v[248:251], v[192:195], v[70:73]
	v_mfma_f32_16x16x32_bf16 v[62:65], v[240:243], v[200:203], v[62:65]
	v_mfma_f32_16x16x32_bf16 v[58:61], v[248:251], v[200:203], v[58:61]
	v_mfma_f32_16x16x32_bf16 v[54:57], v[240:243], v[232:235], v[54:57]
	v_mfma_f32_16x16x32_bf16 v[50:53], v[248:251], v[232:235], v[50:53]
	v_lshl_add_u64 v[158:159], v[204:205], 0, s[74:75]
	s_mov_b32 m0, s1
	s_barrier
	ds_read_b128 v[180:183], v0 offset:16384
	ds_read_b128 v[184:187], v0 offset:17408
	ds_read_b128 v[188:191], v0 offset:18432
	ds_read_b128 v[192:195], v0 offset:19456
	ds_read_b128 v[196:199], v0 offset:20480
	ds_read_b128 v[200:203], v0 offset:21504
	ds_read_b128 v[222:225], v0 offset:22528
	ds_read_b128 v[232:235], v0 offset:23552
	global_load_lds_dwordx4 v[158:159], off
	s_add_i32 m0, s1, 0x1f00
	s_nop 0
	global_load_lds_dwordx4 v[210:211], off offset:256
	s_barrier
	s_waitcnt lgkmcnt(0)
	v_mfma_f32_16x16x32_bf16 v[46:49], v[164:167], v[180:183], v[46:49]
	v_mfma_f32_16x16x32_bf16 v[42:45], v[172:175], v[180:183], v[42:45]
	v_mfma_f32_16x16x32_bf16 v[38:41], v[164:167], v[188:191], v[38:41]
	v_mfma_f32_16x16x32_bf16 v[34:37], v[172:175], v[188:191], v[34:37]
	v_mfma_f32_16x16x32_bf16 v[30:33], v[164:167], v[196:199], v[30:33]
	v_mfma_f32_16x16x32_bf16 v[26:29], v[172:175], v[196:199], v[26:29]
	v_mfma_f32_16x16x32_bf16 v[22:25], v[164:167], v[222:225], v[22:25]
	v_mfma_f32_16x16x32_bf16 v[18:21], v[172:175], v[222:225], v[18:21]
	v_mfma_f32_16x16x32_bf16 v[46:49], v[168:171], v[184:187], v[46:49]
	v_mfma_f32_16x16x32_bf16 v[42:45], v[176:179], v[184:187], v[42:45]
	v_mfma_f32_16x16x32_bf16 v[38:41], v[168:171], v[192:195], v[38:41]
	v_mfma_f32_16x16x32_bf16 v[34:37], v[176:179], v[192:195], v[34:37]
	v_mfma_f32_16x16x32_bf16 v[30:33], v[168:171], v[200:203], v[30:33]
	v_mfma_f32_16x16x32_bf16 v[26:29], v[176:179], v[200:203], v[26:29]
	v_mfma_f32_16x16x32_bf16 v[22:25], v[168:171], v[232:235], v[22:25]
	v_mfma_f32_16x16x32_bf16 v[18:21], v[176:179], v[232:235], v[18:21]
	s_barrier
	s_add_i32 m0, s1, 0x14000
	v_lshl_add_u64 v[154:155], v[216:217], 0, s[18:19]
	global_load_lds_dwordx4 v[154:155], off
	s_add_i32 m0, s1, 0x16000
	v_lshl_add_u64 v[156:157], v[218:219], 0, s[18:19]
	global_load_lds_dwordx4 v[156:157], off
	s_waitcnt vmcnt(6)
	s_barrier
	v_mfma_f32_16x16x32_bf16 v[14:17], v[236:239], v[180:183], v[14:17]
	v_mfma_f32_16x16x32_bf16 v[10:13], v[244:247], v[180:183], v[10:13]
	v_mfma_f32_16x16x32_bf16 v[6:9], v[236:239], v[188:191], v[6:9]
	ds_read_b128 v[164:167], v151 offset:32768
	v_mfma_f32_16x16x32_bf16 v[2:5], v[244:247], v[188:191], v[2:5]
	v_mfma_f32_16x16x32_bf16 v[66:69], v[236:239], v[196:199], v[66:69]
	v_mfma_f32_16x16x32_bf16 v[74:77], v[244:247], v[196:199], v[74:77]
	ds_read_b128 v[168:171], v151 offset:33792
	v_mfma_f32_16x16x32_bf16 v[78:81], v[236:239], v[222:225], v[78:81]
	v_mfma_f32_16x16x32_bf16 v[82:85], v[244:247], v[222:225], v[82:85]
	v_mfma_f32_16x16x32_bf16 v[14:17], v[240:243], v[184:187], v[14:17]
	ds_read_b128 v[172:175], v151 offset:34816
	v_mfma_f32_16x16x32_bf16 v[10:13], v[248:251], v[184:187], v[10:13]
	v_mfma_f32_16x16x32_bf16 v[6:9], v[240:243], v[192:195], v[6:9]
	v_mfma_f32_16x16x32_bf16 v[2:5], v[248:251], v[192:195], v[2:5]
	ds_read_b128 v[176:179], v151 offset:35840
	v_mfma_f32_16x16x32_bf16 v[66:69], v[240:243], v[200:203], v[66:69]
	v_mfma_f32_16x16x32_bf16 v[74:77], v[248:251], v[200:203], v[74:77]
	v_mfma_f32_16x16x32_bf16 v[78:81], v[240:243], v[232:235], v[78:81]
	v_mfma_f32_16x16x32_bf16 v[82:85], v[248:251], v[232:235], v[82:85]
	s_barrier
	s_add_i32 m0, s1, 0x3f80
	ds_read_b128 v[180:183], v0 offset:32768
	ds_read_b128 v[184:187], v0 offset:33792
	ds_read_b128 v[188:191], v0 offset:34816
	ds_read_b128 v[192:195], v0 offset:35840
	ds_read_b128 v[196:199], v0 offset:36864
	ds_read_b128 v[200:203], v0 offset:37888
	ds_read_b128 v[222:225], v0 offset:38912
	ds_read_b128 v[232:235], v0 offset:39936
	global_load_lds_dwordx4 v[228:229], off offset:128
	s_add_i32 m0, s1, 0x5f80
	s_nop 0
	global_load_lds_dwordx4 v[152:153], off offset:128
	s_waitcnt lgkmcnt(8)
	s_barrier
	s_waitcnt lgkmcnt(0)
	v_mfma_f32_16x16x32_bf16 v[126:129], v[164:167], v[180:183], v[126:129]
	v_mfma_f32_16x16x32_bf16 v[122:125], v[172:175], v[180:183], v[122:125]
	v_mfma_f32_16x16x32_bf16 v[118:121], v[164:167], v[188:191], v[118:121]
	ds_read_b128 v[236:239], v151 offset:49152
	v_mfma_f32_16x16x32_bf16 v[114:117], v[172:175], v[188:191], v[114:117]
	v_mfma_f32_16x16x32_bf16 v[110:113], v[164:167], v[196:199], v[110:113]
	v_mfma_f32_16x16x32_bf16 v[106:109], v[172:175], v[196:199], v[106:109]
	ds_read_b128 v[240:243], v151 offset:50176
	v_mfma_f32_16x16x32_bf16 v[102:105], v[164:167], v[222:225], v[102:105]
	v_mfma_f32_16x16x32_bf16 v[98:101], v[172:175], v[222:225], v[98:101]
	v_mfma_f32_16x16x32_bf16 v[126:129], v[168:171], v[184:187], v[126:129]
	ds_read_b128 v[244:247], v151 offset:51200
	v_mfma_f32_16x16x32_bf16 v[122:125], v[176:179], v[184:187], v[122:125]
	v_mfma_f32_16x16x32_bf16 v[118:121], v[168:171], v[192:195], v[118:121]
	v_mfma_f32_16x16x32_bf16 v[114:117], v[176:179], v[192:195], v[114:117]
	ds_read_b128 v[248:251], v151 offset:52224
	v_mfma_f32_16x16x32_bf16 v[110:113], v[168:171], v[200:203], v[110:113]
	v_mfma_f32_16x16x32_bf16 v[106:109], v[176:179], v[200:203], v[106:109]
	v_mfma_f32_16x16x32_bf16 v[102:105], v[168:171], v[232:235], v[102:105]
	v_mfma_f32_16x16x32_bf16 v[98:101], v[176:179], v[232:235], v[98:101]
	s_barrier
	s_add_i32 m0, s1, 0x17e80
	global_load_lds_dwordx4 v[216:217], off offset:384
	s_add_i32 m0, s1, 0x19e80
	s_nop 0
	global_load_lds_dwordx4 v[218:219], off offset:384
	s_barrier
	s_waitcnt lgkmcnt(0)
	v_mfma_f32_16x16x32_bf16 v[94:97], v[236:239], v[180:183], v[94:97]
	v_mfma_f32_16x16x32_bf16 v[90:93], v[244:247], v[180:183], v[90:93]
	v_mfma_f32_16x16x32_bf16 v[86:89], v[236:239], v[188:191], v[86:89]
	v_mfma_f32_16x16x32_bf16 v[70:73], v[244:247], v[188:191], v[70:73]
	v_mfma_f32_16x16x32_bf16 v[62:65], v[236:239], v[196:199], v[62:65]
	v_mfma_f32_16x16x32_bf16 v[58:61], v[244:247], v[196:199], v[58:61]
	v_mfma_f32_16x16x32_bf16 v[54:57], v[236:239], v[222:225], v[54:57]
	v_mfma_f32_16x16x32_bf16 v[50:53], v[244:247], v[222:225], v[50:53]
	v_mfma_f32_16x16x32_bf16 v[94:97], v[240:243], v[184:187], v[94:97]
	v_mfma_f32_16x16x32_bf16 v[90:93], v[248:251], v[184:187], v[90:93]
	v_mfma_f32_16x16x32_bf16 v[86:89], v[240:243], v[192:195], v[86:89]
	v_mfma_f32_16x16x32_bf16 v[70:73], v[248:251], v[192:195], v[70:73]
	v_mfma_f32_16x16x32_bf16 v[62:65], v[240:243], v[200:203], v[62:65]
	v_mfma_f32_16x16x32_bf16 v[58:61], v[248:251], v[200:203], v[58:61]
	v_mfma_f32_16x16x32_bf16 v[54:57], v[240:243], v[232:235], v[54:57]
	v_mfma_f32_16x16x32_bf16 v[50:53], v[248:251], v[232:235], v[50:53]
	s_add_i32 m0, s1, 0x7e80
	s_barrier
	ds_read_b128 v[180:183], v0 offset:49152
	ds_read_b128 v[184:187], v0 offset:50176
	ds_read_b128 v[188:191], v0 offset:51200
	ds_read_b128 v[192:195], v0 offset:52224
	ds_read_b128 v[196:199], v0 offset:53248
	ds_read_b128 v[200:203], v0 offset:54272
	ds_read_b128 v[222:225], v0 offset:55296
	ds_read_b128 v[232:235], v0 offset:56320
	global_load_lds_dwordx4 v[204:205], off offset:384
	s_add_i32 m0, s1, 0x9e80
	s_nop 0
	global_load_lds_dwordx4 v[210:211], off offset:384
	s_barrier
	s_waitcnt lgkmcnt(0)
	v_mfma_f32_16x16x32_bf16 v[46:49], v[164:167], v[180:183], v[46:49]
	v_mfma_f32_16x16x32_bf16 v[42:45], v[172:175], v[180:183], v[42:45]
	v_mfma_f32_16x16x32_bf16 v[38:41], v[164:167], v[188:191], v[38:41]
	v_mfma_f32_16x16x32_bf16 v[34:37], v[172:175], v[188:191], v[34:37]
	v_mfma_f32_16x16x32_bf16 v[30:33], v[164:167], v[196:199], v[30:33]
	v_mfma_f32_16x16x32_bf16 v[26:29], v[172:175], v[196:199], v[26:29]
	v_mfma_f32_16x16x32_bf16 v[22:25], v[164:167], v[222:225], v[22:25]
	v_mfma_f32_16x16x32_bf16 v[18:21], v[172:175], v[222:225], v[18:21]
	v_mfma_f32_16x16x32_bf16 v[46:49], v[168:171], v[184:187], v[46:49]
	v_mfma_f32_16x16x32_bf16 v[42:45], v[176:179], v[184:187], v[42:45]
	v_mfma_f32_16x16x32_bf16 v[38:41], v[168:171], v[192:195], v[38:41]
	v_mfma_f32_16x16x32_bf16 v[34:37], v[176:179], v[192:195], v[34:37]
	v_mfma_f32_16x16x32_bf16 v[30:33], v[168:171], v[200:203], v[30:33]
	v_mfma_f32_16x16x32_bf16 v[26:29], v[176:179], v[200:203], v[26:29]
	v_mfma_f32_16x16x32_bf16 v[22:25], v[168:171], v[232:235], v[22:25]
	v_mfma_f32_16x16x32_bf16 v[18:21], v[176:179], v[232:235], v[18:21]
	s_barrier
	s_add_i32 m0, s1, 0x1bf80
	s_nop 0
	global_load_lds_dwordx4 v[154:155], off offset:128
	s_add_i32 m0, s1, 0x1df80
	s_nop 0
	global_load_lds_dwordx4 v[156:157], off offset:128
	s_waitcnt vmcnt(6)
	s_barrier
	v_mfma_f32_16x16x32_bf16 v[14:17], v[236:239], v[180:183], v[14:17]
	v_mfma_f32_16x16x32_bf16 v[10:13], v[244:247], v[180:183], v[10:13]
	v_mfma_f32_16x16x32_bf16 v[6:9], v[236:239], v[188:191], v[6:9]
	v_mfma_f32_16x16x32_bf16 v[2:5], v[244:247], v[188:191], v[2:5]
	v_mfma_f32_16x16x32_bf16 v[66:69], v[236:239], v[196:199], v[66:69]
	v_mfma_f32_16x16x32_bf16 v[74:77], v[244:247], v[196:199], v[74:77]
	v_mfma_f32_16x16x32_bf16 v[78:81], v[236:239], v[222:225], v[78:81]
	v_mfma_f32_16x16x32_bf16 v[82:85], v[244:247], v[222:225], v[82:85]
	v_mfma_f32_16x16x32_bf16 v[14:17], v[240:243], v[184:187], v[14:17]
	v_mfma_f32_16x16x32_bf16 v[10:13], v[248:251], v[184:187], v[10:13]
	v_mfma_f32_16x16x32_bf16 v[6:9], v[240:243], v[192:195], v[6:9]
	v_mfma_f32_16x16x32_bf16 v[2:5], v[248:251], v[192:195], v[2:5]
	v_mfma_f32_16x16x32_bf16 v[66:69], v[240:243], v[200:203], v[66:69]
	v_mfma_f32_16x16x32_bf16 v[74:77], v[248:251], v[200:203], v[74:77]
	v_mfma_f32_16x16x32_bf16 v[78:81], v[240:243], v[232:235], v[78:81]
	v_mfma_f32_16x16x32_bf16 v[82:85], v[248:251], v[232:235], v[82:85]
	s_add_i32 s0, s0, 2
	s_add_u32 s12, s12, 0x100
	s_addc_u32 s13, s13, 0
	s_cmp_lt_u32 s0, 28
	s_barrier
	s_cbranch_scc1 .LBB0_34
	s_add_i32 s1, s1, 0x1e000
	s_mov_b64 s[12:13], 0xf80
	v_readfirstlane_b32 s0, v162
	v_lshl_add_u64 v[132:133], v[132:133], 0, s[12:13]
	s_mov_b32 m0, s0
	v_readfirstlane_b32 s0, v163
	ds_read_b128 v[134:137], v151
	ds_read_b128 v[138:141], v151 offset:1024
	ds_read_b128 v[152:155], v151 offset:2048
	ds_read_b128 v[156:159], v151 offset:3072
	ds_read_b128 v[164:167], v0
	ds_read_b128 v[168:171], v0 offset:1024
	ds_read_b128 v[172:175], v0 offset:2048
	ds_read_b128 v[176:179], v0 offset:3072
	ds_read_b128 v[180:183], v0 offset:4096
	ds_read_b128 v[184:187], v0 offset:5120
	ds_read_b128 v[188:191], v0 offset:6144
	ds_read_b128 v[192:195], v0 offset:7168
	global_load_lds_dwordx4 v[132:133], off
	v_lshl_add_u64 v[130:131], v[130:131], 0, s[12:13]
	s_mov_b32 m0, s0
	s_nop 0
	global_load_lds_dwordx4 v[130:131], off
	s_barrier
	s_waitcnt lgkmcnt(0)
	s_setprio 1
	s_waitcnt lgkmcnt(0)
	v_mfma_f32_16x16x32_bf16 v[122:125], v[152:155], v[164:167], v[122:125]
	v_mfma_f32_16x16x32_bf16 v[118:121], v[134:137], v[172:175], v[118:121]
	v_mfma_f32_16x16x32_bf16 v[114:117], v[152:155], v[172:175], v[114:117]
	v_mfma_f32_16x16x32_bf16 v[102:105], v[134:137], v[188:191], v[102:105]
	v_mfma_f32_16x16x32_bf16 v[98:101], v[152:155], v[188:191], v[98:101]
	v_mfma_f32_16x16x32_bf16 v[126:129], v[134:137], v[164:167], v[126:129]
	v_mfma_f32_16x16x32_bf16 v[122:125], v[156:159], v[168:171], v[122:125]
	v_mfma_f32_16x16x32_bf16 v[118:121], v[138:141], v[176:179], v[118:121]
	v_mfma_f32_16x16x32_bf16 v[114:117], v[156:159], v[176:179], v[114:117]
	v_mfma_f32_16x16x32_bf16 v[110:113], v[134:137], v[180:183], v[110:113]
	v_mfma_f32_16x16x32_bf16 v[106:109], v[152:155], v[180:183], v[106:109]
	v_mfma_f32_16x16x32_bf16 v[102:105], v[138:141], v[192:195], v[102:105]
	v_mfma_f32_16x16x32_bf16 v[98:101], v[156:159], v[192:195], v[98:101]
	v_mfma_f32_16x16x32_bf16 v[126:129], v[138:141], v[168:171], v[126:129]
	v_mfma_f32_16x16x32_bf16 v[130:133], v[138:141], v[184:187], v[110:113]
	v_mfma_f32_16x16x32_bf16 v[160:163], v[156:159], v[184:187], v[106:109]
	s_setprio 0
	s_barrier
	ds_read_b128 v[106:109], v151 offset:16384
	ds_read_b128 v[110:113], v151 offset:17408
	ds_read_b128 v[196:199], v151 offset:18432
	ds_read_b128 v[200:203], v151 offset:19456
	s_barrier
	s_waitcnt lgkmcnt(0)
	s_setprio 1
	s_waitcnt lgkmcnt(3)
	v_mfma_f32_16x16x32_bf16 v[86:89], v[106:109], v[172:175], v[86:89]
	s_waitcnt lgkmcnt(1)
	v_mfma_f32_16x16x32_bf16 v[70:73], v[196:199], v[172:175], v[70:73]
	v_mfma_f32_16x16x32_bf16 v[62:65], v[106:109], v[180:183], v[62:65]
	v_mfma_f32_16x16x32_bf16 v[58:61], v[196:199], v[180:183], v[58:61]
	v_mfma_f32_16x16x32_bf16 v[54:57], v[106:109], v[188:191], v[54:57]
	v_mfma_f32_16x16x32_bf16 v[50:53], v[196:199], v[188:191], v[50:53]
	v_mfma_f32_16x16x32_bf16 v[94:97], v[106:109], v[164:167], v[94:97]
	v_mfma_f32_16x16x32_bf16 v[90:93], v[196:199], v[164:167], v[90:93]
	v_mfma_f32_16x16x32_bf16 v[86:89], v[110:113], v[176:179], v[86:89]
	s_waitcnt lgkmcnt(0)
	v_mfma_f32_16x16x32_bf16 v[70:73], v[200:203], v[176:179], v[70:73]
	v_mfma_f32_16x16x32_bf16 v[62:65], v[110:113], v[184:187], v[62:65]
	v_mfma_f32_16x16x32_bf16 v[58:61], v[200:203], v[184:187], v[58:61]
	v_mfma_f32_16x16x32_bf16 v[54:57], v[110:113], v[192:195], v[54:57]
	v_mfma_f32_16x16x32_bf16 v[50:53], v[200:203], v[192:195], v[50:53]
	v_mfma_f32_16x16x32_bf16 v[222:225], v[110:113], v[168:171], v[94:97]
	v_mfma_f32_16x16x32_bf16 v[164:167], v[200:203], v[168:171], v[90:93]
	s_setprio 0
	s_barrier
	s_nop 0
	ds_read_b128 v[90:93], v0 offset:16384
	ds_read_b128 v[94:97], v0 offset:17408
	ds_read_b128 v[168:171], v0 offset:18432
	ds_read_b128 v[172:175], v0 offset:19456
	ds_read_b128 v[176:179], v0 offset:20480
	ds_read_b128 v[180:183], v0 offset:21504
	ds_read_b128 v[184:187], v0 offset:22528
	ds_read_b128 v[188:191], v0 offset:23552
	s_waitcnt vmcnt(4)
	s_barrier
	s_waitcnt lgkmcnt(0)
	s_setprio 1
	s_waitcnt lgkmcnt(7)
	v_mfma_f32_16x16x32_bf16 v[46:49], v[134:137], v[90:93], v[46:49]
	v_mfma_f32_16x16x32_bf16 v[42:45], v[152:155], v[90:93], v[42:45]
	s_waitcnt lgkmcnt(5)
	v_mfma_f32_16x16x32_bf16 v[38:41], v[134:137], v[168:171], v[38:41]
	v_mfma_f32_16x16x32_bf16 v[34:37], v[152:155], v[168:171], v[34:37]
	s_waitcnt lgkmcnt(3)
	v_mfma_f32_16x16x32_bf16 v[30:33], v[134:137], v[176:179], v[30:33]
	v_mfma_f32_16x16x32_bf16 v[26:29], v[152:155], v[176:179], v[26:29]
	s_waitcnt lgkmcnt(1)
	v_mfma_f32_16x16x32_bf16 v[22:25], v[134:137], v[184:187], v[22:25]
	v_mfma_f32_16x16x32_bf16 v[18:21], v[152:155], v[184:187], v[18:21]
	v_mfma_f32_16x16x32_bf16 v[46:49], v[138:141], v[94:97], v[46:49]
	v_mfma_f32_16x16x32_bf16 v[42:45], v[156:159], v[94:97], v[42:45]
	v_mfma_f32_16x16x32_bf16 v[38:41], v[138:141], v[172:175], v[38:41]
	v_mfma_f32_16x16x32_bf16 v[34:37], v[156:159], v[172:175], v[34:37]
	v_mfma_f32_16x16x32_bf16 v[30:33], v[138:141], v[180:183], v[30:33]
	v_mfma_f32_16x16x32_bf16 v[26:29], v[156:159], v[180:183], v[26:29]
	s_waitcnt lgkmcnt(0)
	v_mfma_f32_16x16x32_bf16 v[22:25], v[138:141], v[188:191], v[22:25]
	v_mfma_f32_16x16x32_bf16 v[18:21], v[156:159], v[188:191], v[18:21]
	s_setprio 0
	s_setprio 1
	v_mfma_f32_16x16x32_bf16 v[10:13], v[196:199], v[90:93], v[10:13]
	v_mfma_f32_16x16x32_bf16 v[152:155], v[200:203], v[94:97], v[10:13]
	v_mfma_f32_16x16x32_bf16 v[10:13], v[106:109], v[176:179], v[66:69]
	v_mfma_f32_16x16x32_bf16 v[156:159], v[110:113], v[180:183], v[10:13]
	v_mfma_f32_16x16x32_bf16 v[10:13], v[196:199], v[176:179], v[74:77]
	v_mfma_f32_16x16x32_bf16 v[6:9], v[106:109], v[168:171], v[6:9]
	v_mfma_f32_16x16x32_bf16 v[2:5], v[196:199], v[168:171], v[2:5]
	v_mfma_f32_16x16x32_bf16 v[168:171], v[200:203], v[180:183], v[10:13]
	v_mfma_f32_16x16x32_bf16 v[10:13], v[106:109], v[184:187], v[78:81]
	v_mfma_f32_16x16x32_bf16 v[14:17], v[106:109], v[90:93], v[14:17]
	v_mfma_f32_16x16x32_bf16 v[6:9], v[110:113], v[172:175], v[6:9]
	v_mfma_f32_16x16x32_bf16 v[2:5], v[200:203], v[172:175], v[2:5]
	v_mfma_f32_16x16x32_bf16 v[172:175], v[110:113], v[188:191], v[10:13]
	v_mfma_f32_16x16x32_bf16 v[10:13], v[196:199], v[184:187], v[82:85]
	v_mfma_f32_16x16x32_bf16 v[134:137], v[110:113], v[94:97], v[14:17]
	v_mfma_f32_16x16x32_bf16 v[176:179], v[200:203], v[188:191], v[10:13]
	s_setprio 0
	s_barrier
	s_nop 3
	ds_read_b128 v[10:13], v151 offset:32768
	ds_read_b128 v[14:17], v151 offset:33792
	ds_read_b128 v[180:183], v151 offset:34816
	ds_read_b128 v[184:187], v151 offset:35840
	ds_read_b128 v[66:69], v0 offset:32768
	ds_read_b128 v[82:85], v0 offset:33792
	ds_read_b128 v[188:191], v0 offset:34816
	ds_read_b128 v[192:195], v0 offset:35840
	ds_read_b128 v[196:199], v0 offset:36864
	ds_read_b128 v[200:203], v0 offset:37888
	ds_read_b128 v[232:235], v0 offset:38912
	ds_read_b128 v[236:239], v0 offset:39936
	s_waitcnt vmcnt(2)
	s_barrier
	s_waitcnt lgkmcnt(0)
	s_setprio 1
	s_waitcnt lgkmcnt(7)
	v_mfma_f32_16x16x32_bf16 v[74:77], v[10:13], v[66:69], v[126:129]
	s_waitcnt lgkmcnt(6)
	v_mfma_f32_16x16x32_bf16 v[138:141], v[14:17], v[82:85], v[74:77]
	v_mfma_f32_16x16x32_bf16 v[74:77], v[180:183], v[66:69], v[122:125]
	v_mfma_f32_16x16x32_bf16 v[122:125], v[184:187], v[82:85], v[74:77]
	s_waitcnt lgkmcnt(5)
	v_mfma_f32_16x16x32_bf16 v[74:77], v[10:13], v[188:191], v[118:121]
	s_waitcnt lgkmcnt(4)
	v_mfma_f32_16x16x32_bf16 v[110:113], v[14:17], v[192:195], v[74:77]
	v_mfma_f32_16x16x32_bf16 v[74:77], v[180:183], v[188:191], v[114:117]
	v_mfma_f32_16x16x32_bf16 v[106:109], v[184:187], v[192:195], v[74:77]
	s_waitcnt lgkmcnt(3)
	v_mfma_f32_16x16x32_bf16 v[74:77], v[10:13], v[196:199], v[130:133]
	s_waitcnt lgkmcnt(2)
	v_mfma_f32_16x16x32_bf16 v[94:97], v[14:17], v[200:203], v[74:77]
	v_mfma_f32_16x16x32_bf16 v[74:77], v[180:183], v[196:199], v[160:163]
	v_mfma_f32_16x16x32_bf16 v[90:93], v[184:187], v[200:203], v[74:77]
	s_waitcnt lgkmcnt(1)
	v_mfma_f32_16x16x32_bf16 v[74:77], v[10:13], v[232:235], v[102:105]
	s_waitcnt lgkmcnt(0)
	v_mfma_f32_16x16x32_bf16 v[78:81], v[14:17], v[236:239], v[74:77]
	v_mfma_f32_16x16x32_bf16 v[74:77], v[180:183], v[232:235], v[98:101]
	v_mfma_f32_16x16x32_bf16 v[74:77], v[184:187], v[236:239], v[74:77]
	s_setprio 0
	s_barrier
	ds_read_b128 v[126:129], v151 offset:49152
	ds_read_b128 v[130:133], v151 offset:50176
	ds_read_b128 v[160:163], v151 offset:51200
	ds_read_b128 v[148:151], v151 offset:52224
	s_waitcnt vmcnt(0)
	s_barrier
	s_waitcnt lgkmcnt(0)
	s_setprio 1
	s_waitcnt lgkmcnt(3)
	v_mfma_f32_16x16x32_bf16 v[98:101], v[126:129], v[66:69], v[222:225]
	s_waitcnt lgkmcnt(1)
	v_mfma_f32_16x16x32_bf16 v[66:69], v[160:163], v[66:69], v[164:167]
	s_waitcnt lgkmcnt(0)
	v_mfma_f32_16x16x32_bf16 v[114:117], v[148:151], v[82:85], v[66:69]
	v_mfma_f32_16x16x32_bf16 v[66:69], v[126:129], v[188:191], v[86:89]
	v_mfma_f32_16x16x32_bf16 v[102:105], v[130:133], v[192:195], v[66:69]
	v_mfma_f32_16x16x32_bf16 v[66:69], v[160:163], v[188:191], v[70:73]
	v_mfma_f32_16x16x32_bf16 v[62:65], v[126:129], v[196:199], v[62:65]
	v_mfma_f32_16x16x32_bf16 v[58:61], v[160:163], v[196:199], v[58:61]
	v_mfma_f32_16x16x32_bf16 v[54:57], v[126:129], v[232:235], v[54:57]
	v_mfma_f32_16x16x32_bf16 v[50:53], v[160:163], v[232:235], v[50:53]
	v_mfma_f32_16x16x32_bf16 v[118:121], v[130:133], v[82:85], v[98:101]
	v_mfma_f32_16x16x32_bf16 v[98:101], v[148:151], v[192:195], v[66:69]
	v_mfma_f32_16x16x32_bf16 v[86:89], v[130:133], v[200:203], v[62:65]
	v_mfma_f32_16x16x32_bf16 v[82:85], v[148:151], v[200:203], v[58:61]
	v_mfma_f32_16x16x32_bf16 v[70:73], v[130:133], v[236:239], v[54:57]
	v_mfma_f32_16x16x32_bf16 v[66:69], v[148:151], v[236:239], v[50:53]
	s_setprio 0
	s_barrier
	s_nop 0
	ds_read_b128 v[50:53], v0 offset:49152
	ds_read_b128 v[164:167], v0 offset:50176
	ds_read_b128 v[188:191], v0 offset:51200
	ds_read_b128 v[192:195], v0 offset:52224
	ds_read_b128 v[196:199], v0 offset:53248
	ds_read_b128 v[200:203], v0 offset:54272
	ds_read_b128 v[222:225], v0 offset:55296
	ds_read_b128 v[232:235], v0 offset:56320
	s_barrier
	s_waitcnt lgkmcnt(0)
	s_setprio 1
	s_waitcnt lgkmcnt(7)
	v_mfma_f32_16x16x32_bf16 v[46:49], v[10:13], v[50:53], v[46:49]
	s_waitcnt lgkmcnt(5)
	v_mfma_f32_16x16x32_bf16 v[38:41], v[10:13], v[188:191], v[38:41]
	s_waitcnt lgkmcnt(3)
	v_mfma_f32_16x16x32_bf16 v[30:33], v[10:13], v[196:199], v[30:33]
	s_waitcnt lgkmcnt(1)
	v_mfma_f32_16x16x32_bf16 v[10:13], v[10:13], v[222:225], v[22:25]
	v_mfma_f32_16x16x32_bf16 v[62:65], v[14:17], v[164:167], v[46:49]
	v_mfma_f32_16x16x32_bf16 v[42:45], v[180:183], v[50:53], v[42:45]
	v_mfma_f32_16x16x32_bf16 v[46:49], v[14:17], v[192:195], v[38:41]
	v_mfma_f32_16x16x32_bf16 v[34:37], v[180:183], v[188:191], v[34:37]
	v_mfma_f32_16x16x32_bf16 v[30:33], v[14:17], v[200:203], v[30:33]
	v_mfma_f32_16x16x32_bf16 v[26:29], v[180:183], v[196:199], v[26:29]
	s_waitcnt lgkmcnt(0)
	v_mfma_f32_16x16x32_bf16 v[14:17], v[14:17], v[232:235], v[10:13]
	v_mfma_f32_16x16x32_bf16 v[10:13], v[180:183], v[222:225], v[18:21]
	v_mfma_f32_16x16x32_bf16 v[58:61], v[184:187], v[164:167], v[42:45]
	v_mfma_f32_16x16x32_bf16 v[42:45], v[184:187], v[192:195], v[34:37]
	v_mfma_f32_16x16x32_bf16 v[26:29], v[184:187], v[200:203], v[26:29]
	v_mfma_f32_16x16x32_bf16 v[10:13], v[184:187], v[232:235], v[10:13]
	s_setprio 0
	s_setprio 1
	v_mfma_f32_16x16x32_bf16 v[2:5], v[160:163], v[188:191], v[2:5]
	v_mfma_f32_16x16x32_bf16 v[18:21], v[126:129], v[50:53], v[134:137]
	v_mfma_f32_16x16x32_bf16 v[34:37], v[148:151], v[192:195], v[2:5]
	v_mfma_f32_16x16x32_bf16 v[2:5], v[126:129], v[196:199], v[156:159]
	v_mfma_f32_16x16x32_bf16 v[54:57], v[130:133], v[164:167], v[18:21]
	v_mfma_f32_16x16x32_bf16 v[18:21], v[160:163], v[50:53], v[152:155]
	v_mfma_f32_16x16x32_bf16 v[22:25], v[130:133], v[200:203], v[2:5]
	v_mfma_f32_16x16x32_bf16 v[2:5], v[160:163], v[196:199], v[168:171]
	v_mfma_f32_16x16x32_bf16 v[50:53], v[148:151], v[164:167], v[18:21]
	v_mfma_f32_16x16x32_bf16 v[6:9], v[126:129], v[188:191], v[6:9]
	v_mfma_f32_16x16x32_bf16 v[18:21], v[148:151], v[200:203], v[2:5]
	v_mfma_f32_16x16x32_bf16 v[2:5], v[126:129], v[222:225], v[172:175]
	v_mfma_f32_16x16x32_bf16 v[38:41], v[130:133], v[192:195], v[6:9]
	v_mfma_f32_16x16x32_bf16 v[6:9], v[130:133], v[232:235], v[2:5]
	v_mfma_f32_16x16x32_bf16 v[2:5], v[160:163], v[222:225], v[176:179]
	v_mfma_f32_16x16x32_bf16 v[2:5], v[148:151], v[232:235], v[2:5]
	s_setprio 0
	s_movk_i32 s0, 0x100
	v_cmp_gt_u32_e32 vcc, s0, v142
	s_barrier
	s_and_saveexec_b64 s[0:1], vcc
	s_cbranch_execz .LBB0_37
	s_barrier

.LBB0_85:
	ds_read_b128 v[164:167], v151
	ds_read_b128 v[168:171], v151 offset:1024
	ds_read_b128 v[172:175], v151 offset:2048
	ds_read_b128 v[176:179], v151 offset:3072
	v_lshl_add_u64 v[204:205], v[138:139], 0, s[10:11]
	v_lshl_add_u64 v[228:229], v[204:205], 0, s[60:61]
	s_add_i32 m0, s1, 0xc000
	ds_read_b128 v[180:183], v0
	ds_read_b128 v[184:187], v0 offset:1024
	ds_read_b128 v[188:191], v0 offset:2048
	ds_read_b128 v[192:195], v0 offset:3072
	ds_read_b128 v[196:199], v0 offset:4096
	ds_read_b128 v[200:203], v0 offset:5120
	ds_read_b128 v[222:225], v0 offset:6144
	ds_read_b128 v[232:235], v0 offset:7168
	global_load_lds_dwordx4 v[228:229], off
	v_lshl_add_u64 v[210:211], v[140:141], 0, s[10:11]
	s_add_i32 m0, s1, 0xe000
	v_lshl_add_u64 v[152:153], v[210:211], 0, s[60:61]
	global_load_lds_dwordx4 v[152:153], off
	s_waitcnt lgkmcnt(8)
	s_barrier
	s_waitcnt lgkmcnt(0)
	v_mfma_f32_16x16x32_bf16 v[126:129], v[164:167], v[180:183], v[126:129]
	v_mfma_f32_16x16x32_bf16 v[122:125], v[172:175], v[180:183], v[122:125]
	v_mfma_f32_16x16x32_bf16 v[118:121], v[164:167], v[188:191], v[118:121]
	ds_read_b128 v[236:239], v151 offset:16384
	v_mfma_f32_16x16x32_bf16 v[114:117], v[172:175], v[188:191], v[114:117]
	v_mfma_f32_16x16x32_bf16 v[110:113], v[164:167], v[196:199], v[110:113]
	v_mfma_f32_16x16x32_bf16 v[106:109], v[172:175], v[196:199], v[106:109]
	ds_read_b128 v[240:243], v151 offset:17408
	v_mfma_f32_16x16x32_bf16 v[102:105], v[164:167], v[222:225], v[102:105]
	v_mfma_f32_16x16x32_bf16 v[98:101], v[172:175], v[222:225], v[98:101]
	v_mfma_f32_16x16x32_bf16 v[126:129], v[168:171], v[184:187], v[126:129]
	ds_read_b128 v[244:247], v151 offset:18432
	v_mfma_f32_16x16x32_bf16 v[122:125], v[176:179], v[184:187], v[122:125]
	v_mfma_f32_16x16x32_bf16 v[118:121], v[168:171], v[192:195], v[118:121]
	v_mfma_f32_16x16x32_bf16 v[114:117], v[176:179], v[192:195], v[114:117]
	ds_read_b128 v[248:251], v151 offset:19456
	v_mfma_f32_16x16x32_bf16 v[110:113], v[168:171], v[200:203], v[110:113]
	v_mfma_f32_16x16x32_bf16 v[106:109], v[176:179], v[200:203], v[106:109]
	v_mfma_f32_16x16x32_bf16 v[102:105], v[168:171], v[232:235], v[102:105]
	v_mfma_f32_16x16x32_bf16 v[98:101], v[176:179], v[232:235], v[98:101]
	s_barrier
	v_lshl_add_u64 v[216:217], v[134:135], 0, s[10:11]
	s_add_i32 m0, s1, 0xff00
	global_load_lds_dwordx4 v[216:217], off offset:256
	s_add_i32 m0, s1, 0x11f00
	v_lshl_add_u64 v[218:219], v[136:137], 0, s[10:11]
	global_load_lds_dwordx4 v[218:219], off offset:256
	s_barrier
	s_waitcnt lgkmcnt(0)
	v_mfma_f32_16x16x32_bf16 v[94:97], v[236:239], v[180:183], v[94:97]
	v_mfma_f32_16x16x32_bf16 v[90:93], v[244:247], v[180:183], v[90:93]
	v_mfma_f32_16x16x32_bf16 v[86:89], v[236:239], v[188:191], v[86:89]
	v_mfma_f32_16x16x32_bf16 v[82:85], v[244:247], v[188:191], v[82:85]
	v_mfma_f32_16x16x32_bf16 v[78:81], v[236:239], v[196:199], v[78:81]
	v_mfma_f32_16x16x32_bf16 v[74:77], v[244:247], v[196:199], v[74:77]
	v_mfma_f32_16x16x32_bf16 v[70:73], v[236:239], v[222:225], v[70:73]
	v_mfma_f32_16x16x32_bf16 v[66:69], v[244:247], v[222:225], v[66:69]
	v_mfma_f32_16x16x32_bf16 v[94:97], v[240:243], v[184:187], v[94:97]
	v_mfma_f32_16x16x32_bf16 v[90:93], v[248:251], v[184:187], v[90:93]
	v_mfma_f32_16x16x32_bf16 v[86:89], v[240:243], v[192:195], v[86:89]
	v_mfma_f32_16x16x32_bf16 v[82:85], v[248:251], v[192:195], v[82:85]
	v_mfma_f32_16x16x32_bf16 v[78:81], v[240:243], v[200:203], v[78:81]
	v_mfma_f32_16x16x32_bf16 v[74:77], v[248:251], v[200:203], v[74:77]
	v_mfma_f32_16x16x32_bf16 v[70:73], v[240:243], v[232:235], v[70:73]
	v_mfma_f32_16x16x32_bf16 v[66:69], v[248:251], v[232:235], v[66:69]
	v_lshl_add_u64 v[158:159], v[204:205], 0, s[74:75]
	s_mov_b32 m0, s1
	s_barrier
	ds_read_b128 v[180:183], v0 offset:16384
	ds_read_b128 v[184:187], v0 offset:17408
	ds_read_b128 v[188:191], v0 offset:18432
	ds_read_b128 v[192:195], v0 offset:19456
	ds_read_b128 v[196:199], v0 offset:20480
	ds_read_b128 v[200:203], v0 offset:21504
	ds_read_b128 v[222:225], v0 offset:22528
	ds_read_b128 v[232:235], v0 offset:23552
	global_load_lds_dwordx4 v[158:159], off
	s_add_i32 m0, s1, 0x1f00
	s_nop 0
	global_load_lds_dwordx4 v[210:211], off offset:256
	s_barrier
	s_waitcnt lgkmcnt(0)
	v_mfma_f32_16x16x32_bf16 v[62:65], v[164:167], v[180:183], v[62:65]
	v_mfma_f32_16x16x32_bf16 v[58:61], v[172:175], v[180:183], v[58:61]
	v_mfma_f32_16x16x32_bf16 v[54:57], v[164:167], v[188:191], v[54:57]
	v_mfma_f32_16x16x32_bf16 v[50:53], v[172:175], v[188:191], v[50:53]
	v_mfma_f32_16x16x32_bf16 v[46:49], v[164:167], v[196:199], v[46:49]
	v_mfma_f32_16x16x32_bf16 v[42:45], v[172:175], v[196:199], v[42:45]
	v_mfma_f32_16x16x32_bf16 v[38:41], v[164:167], v[222:225], v[38:41]
	v_mfma_f32_16x16x32_bf16 v[34:37], v[172:175], v[222:225], v[34:37]
	v_mfma_f32_16x16x32_bf16 v[62:65], v[168:171], v[184:187], v[62:65]
	v_mfma_f32_16x16x32_bf16 v[58:61], v[176:179], v[184:187], v[58:61]
	v_mfma_f32_16x16x32_bf16 v[54:57], v[168:171], v[192:195], v[54:57]
	v_mfma_f32_16x16x32_bf16 v[50:53], v[176:179], v[192:195], v[50:53]
	v_mfma_f32_16x16x32_bf16 v[46:49], v[168:171], v[200:203], v[46:49]
	v_mfma_f32_16x16x32_bf16 v[42:45], v[176:179], v[200:203], v[42:45]
	v_mfma_f32_16x16x32_bf16 v[38:41], v[168:171], v[232:235], v[38:41]
	v_mfma_f32_16x16x32_bf16 v[34:37], v[176:179], v[232:235], v[34:37]
	s_barrier
	s_add_i32 m0, s1, 0x14000
	v_lshl_add_u64 v[154:155], v[216:217], 0, s[18:19]
	global_load_lds_dwordx4 v[154:155], off
	s_add_i32 m0, s1, 0x16000
	v_lshl_add_u64 v[156:157], v[218:219], 0, s[18:19]
	global_load_lds_dwordx4 v[156:157], off
	s_waitcnt vmcnt(6)
	s_barrier
	v_mfma_f32_16x16x32_bf16 v[30:33], v[236:239], v[180:183], v[30:33]
	v_mfma_f32_16x16x32_bf16 v[26:29], v[244:247], v[180:183], v[26:29]
	v_mfma_f32_16x16x32_bf16 v[22:25], v[236:239], v[188:191], v[22:25]
	ds_read_b128 v[164:167], v151 offset:32768
	v_mfma_f32_16x16x32_bf16 v[18:21], v[244:247], v[188:191], v[18:21]
	v_mfma_f32_16x16x32_bf16 v[14:17], v[236:239], v[196:199], v[14:17]
	v_mfma_f32_16x16x32_bf16 v[10:13], v[244:247], v[196:199], v[10:13]
	ds_read_b128 v[168:171], v151 offset:33792
	v_mfma_f32_16x16x32_bf16 v[6:9], v[236:239], v[222:225], v[6:9]
	v_mfma_f32_16x16x32_bf16 v[2:5], v[244:247], v[222:225], v[2:5]
	v_mfma_f32_16x16x32_bf16 v[30:33], v[240:243], v[184:187], v[30:33]
	ds_read_b128 v[172:175], v151 offset:34816
	v_mfma_f32_16x16x32_bf16 v[26:29], v[248:251], v[184:187], v[26:29]
	v_mfma_f32_16x16x32_bf16 v[22:25], v[240:243], v[192:195], v[22:25]
	v_mfma_f32_16x16x32_bf16 v[18:21], v[248:251], v[192:195], v[18:21]
	ds_read_b128 v[176:179], v151 offset:35840
	v_mfma_f32_16x16x32_bf16 v[14:17], v[240:243], v[200:203], v[14:17]
	v_mfma_f32_16x16x32_bf16 v[10:13], v[248:251], v[200:203], v[10:13]
	v_mfma_f32_16x16x32_bf16 v[6:9], v[240:243], v[232:235], v[6:9]
	v_mfma_f32_16x16x32_bf16 v[2:5], v[248:251], v[232:235], v[2:5]
	s_barrier
	s_add_i32 m0, s1, 0x3f80
	ds_read_b128 v[180:183], v0 offset:32768
	ds_read_b128 v[184:187], v0 offset:33792
	ds_read_b128 v[188:191], v0 offset:34816
	ds_read_b128 v[192:195], v0 offset:35840
	ds_read_b128 v[196:199], v0 offset:36864
	ds_read_b128 v[200:203], v0 offset:37888
	ds_read_b128 v[222:225], v0 offset:38912
	ds_read_b128 v[232:235], v0 offset:39936
	global_load_lds_dwordx4 v[228:229], off offset:128
	s_add_i32 m0, s1, 0x5f80
	s_nop 0
	global_load_lds_dwordx4 v[152:153], off offset:128
	s_waitcnt lgkmcnt(8)
	s_barrier
	s_waitcnt lgkmcnt(0)
	v_mfma_f32_16x16x32_bf16 v[126:129], v[164:167], v[180:183], v[126:129]
	v_mfma_f32_16x16x32_bf16 v[122:125], v[172:175], v[180:183], v[122:125]
	v_mfma_f32_16x16x32_bf16 v[118:121], v[164:167], v[188:191], v[118:121]
	ds_read_b128 v[236:239], v151 offset:49152
	v_mfma_f32_16x16x32_bf16 v[114:117], v[172:175], v[188:191], v[114:117]
	v_mfma_f32_16x16x32_bf16 v[110:113], v[164:167], v[196:199], v[110:113]
	v_mfma_f32_16x16x32_bf16 v[106:109], v[172:175], v[196:199], v[106:109]
	ds_read_b128 v[240:243], v151 offset:50176
	v_mfma_f32_16x16x32_bf16 v[102:105], v[164:167], v[222:225], v[102:105]
	v_mfma_f32_16x16x32_bf16 v[98:101], v[172:175], v[222:225], v[98:101]
	v_mfma_f32_16x16x32_bf16 v[126:129], v[168:171], v[184:187], v[126:129]
	ds_read_b128 v[244:247], v151 offset:51200
	v_mfma_f32_16x16x32_bf16 v[122:125], v[176:179], v[184:187], v[122:125]
	v_mfma_f32_16x16x32_bf16 v[118:121], v[168:171], v[192:195], v[118:121]
	v_mfma_f32_16x16x32_bf16 v[114:117], v[176:179], v[192:195], v[114:117]
	ds_read_b128 v[248:251], v151 offset:52224
	v_mfma_f32_16x16x32_bf16 v[110:113], v[168:171], v[200:203], v[110:113]
	v_mfma_f32_16x16x32_bf16 v[106:109], v[176:179], v[200:203], v[106:109]
	v_mfma_f32_16x16x32_bf16 v[102:105], v[168:171], v[232:235], v[102:105]
	v_mfma_f32_16x16x32_bf16 v[98:101], v[176:179], v[232:235], v[98:101]
	s_barrier
	s_add_i32 m0, s1, 0x17e80
	global_load_lds_dwordx4 v[216:217], off offset:384
	s_add_i32 m0, s1, 0x19e80
	s_nop 0
	global_load_lds_dwordx4 v[218:219], off offset:384
	s_barrier
	s_waitcnt lgkmcnt(0)
	v_mfma_f32_16x16x32_bf16 v[94:97], v[236:239], v[180:183], v[94:97]
	v_mfma_f32_16x16x32_bf16 v[90:93], v[244:247], v[180:183], v[90:93]
	v_mfma_f32_16x16x32_bf16 v[86:89], v[236:239], v[188:191], v[86:89]
	v_mfma_f32_16x16x32_bf16 v[82:85], v[244:247], v[188:191], v[82:85]
	v_mfma_f32_16x16x32_bf16 v[78:81], v[236:239], v[196:199], v[78:81]
	v_mfma_f32_16x16x32_bf16 v[74:77], v[244:247], v[196:199], v[74:77]
	v_mfma_f32_16x16x32_bf16 v[70:73], v[236:239], v[222:225], v[70:73]
	v_mfma_f32_16x16x32_bf16 v[66:69], v[244:247], v[222:225], v[66:69]
	v_mfma_f32_16x16x32_bf16 v[94:97], v[240:243], v[184:187], v[94:97]
	v_mfma_f32_16x16x32_bf16 v[90:93], v[248:251], v[184:187], v[90:93]
	v_mfma_f32_16x16x32_bf16 v[86:89], v[240:243], v[192:195], v[86:89]
	v_mfma_f32_16x16x32_bf16 v[82:85], v[248:251], v[192:195], v[82:85]
	v_mfma_f32_16x16x32_bf16 v[78:81], v[240:243], v[200:203], v[78:81]
	v_mfma_f32_16x16x32_bf16 v[74:77], v[248:251], v[200:203], v[74:77]
	v_mfma_f32_16x16x32_bf16 v[70:73], v[240:243], v[232:235], v[70:73]
	v_mfma_f32_16x16x32_bf16 v[66:69], v[248:251], v[232:235], v[66:69]
	s_add_i32 m0, s1, 0x7e80
	s_barrier
	ds_read_b128 v[180:183], v0 offset:49152
	ds_read_b128 v[184:187], v0 offset:50176
	ds_read_b128 v[188:191], v0 offset:51200
	ds_read_b128 v[192:195], v0 offset:52224
	ds_read_b128 v[196:199], v0 offset:53248
	ds_read_b128 v[200:203], v0 offset:54272
	ds_read_b128 v[222:225], v0 offset:55296
	ds_read_b128 v[232:235], v0 offset:56320
	global_load_lds_dwordx4 v[204:205], off offset:384
	s_add_i32 m0, s1, 0x9e80
	s_nop 0
	global_load_lds_dwordx4 v[210:211], off offset:384
	s_barrier
	s_waitcnt lgkmcnt(0)
	v_mfma_f32_16x16x32_bf16 v[62:65], v[164:167], v[180:183], v[62:65]
	v_mfma_f32_16x16x32_bf16 v[58:61], v[172:175], v[180:183], v[58:61]
	v_mfma_f32_16x16x32_bf16 v[54:57], v[164:167], v[188:191], v[54:57]
	v_mfma_f32_16x16x32_bf16 v[50:53], v[172:175], v[188:191], v[50:53]
	v_mfma_f32_16x16x32_bf16 v[46:49], v[164:167], v[196:199], v[46:49]
	v_mfma_f32_16x16x32_bf16 v[42:45], v[172:175], v[196:199], v[42:45]
	v_mfma_f32_16x16x32_bf16 v[38:41], v[164:167], v[222:225], v[38:41]
	v_mfma_f32_16x16x32_bf16 v[34:37], v[172:175], v[222:225], v[34:37]
	v_mfma_f32_16x16x32_bf16 v[62:65], v[168:171], v[184:187], v[62:65]
	v_mfma_f32_16x16x32_bf16 v[58:61], v[176:179], v[184:187], v[58:61]
	v_mfma_f32_16x16x32_bf16 v[54:57], v[168:171], v[192:195], v[54:57]
	v_mfma_f32_16x16x32_bf16 v[50:53], v[176:179], v[192:195], v[50:53]
	v_mfma_f32_16x16x32_bf16 v[46:49], v[168:171], v[200:203], v[46:49]
	v_mfma_f32_16x16x32_bf16 v[42:45], v[176:179], v[200:203], v[42:45]
	v_mfma_f32_16x16x32_bf16 v[38:41], v[168:171], v[232:235], v[38:41]
	v_mfma_f32_16x16x32_bf16 v[34:37], v[176:179], v[232:235], v[34:37]
	s_barrier
	s_add_i32 m0, s1, 0x1bf80
	s_nop 0
	global_load_lds_dwordx4 v[154:155], off offset:128
	s_add_i32 m0, s1, 0x1df80
	s_nop 0
	global_load_lds_dwordx4 v[156:157], off offset:128
	s_waitcnt vmcnt(6)
	s_barrier
	v_mfma_f32_16x16x32_bf16 v[30:33], v[236:239], v[180:183], v[30:33]
	v_mfma_f32_16x16x32_bf16 v[26:29], v[244:247], v[180:183], v[26:29]
	v_mfma_f32_16x16x32_bf16 v[22:25], v[236:239], v[188:191], v[22:25]
	v_mfma_f32_16x16x32_bf16 v[18:21], v[244:247], v[188:191], v[18:21]
	v_mfma_f32_16x16x32_bf16 v[14:17], v[236:239], v[196:199], v[14:17]
	v_mfma_f32_16x16x32_bf16 v[10:13], v[244:247], v[196:199], v[10:13]
	v_mfma_f32_16x16x32_bf16 v[6:9], v[236:239], v[222:225], v[6:9]
	v_mfma_f32_16x16x32_bf16 v[2:5], v[244:247], v[222:225], v[2:5]
	v_mfma_f32_16x16x32_bf16 v[30:33], v[240:243], v[184:187], v[30:33]
	v_mfma_f32_16x16x32_bf16 v[26:29], v[248:251], v[184:187], v[26:29]
	v_mfma_f32_16x16x32_bf16 v[22:25], v[240:243], v[192:195], v[22:25]
	v_mfma_f32_16x16x32_bf16 v[18:21], v[248:251], v[192:195], v[18:21]
	v_mfma_f32_16x16x32_bf16 v[14:17], v[240:243], v[200:203], v[14:17]
	v_mfma_f32_16x16x32_bf16 v[10:13], v[248:251], v[200:203], v[10:13]
	v_mfma_f32_16x16x32_bf16 v[6:9], v[240:243], v[232:235], v[6:9]
	v_mfma_f32_16x16x32_bf16 v[2:5], v[248:251], v[232:235], v[2:5]
	s_add_i32 s0, s0, 2
	s_add_u32 s10, s10, 0x100
	s_addc_u32 s11, s11, 0
	s_cmp_lt_u32 s0, 28
	s_barrier
	s_cbranch_scc1 .LBB0_85
	s_add_i32 s1, s1, 0x1e000
	s_mov_b64 s[10:11], 0xf80
	v_readfirstlane_b32 s0, v162
	v_lshl_add_u64 v[132:133], v[132:133], 0, s[10:11]
	s_mov_b32 m0, s0
	v_readfirstlane_b32 s0, v163
	ds_read_b128 v[134:137], v151
	ds_read_b128 v[138:141], v151 offset:1024
	ds_read_b128 v[152:155], v151 offset:2048
	ds_read_b128 v[156:159], v151 offset:3072
	ds_read_b128 v[164:167], v0
	ds_read_b128 v[168:171], v0 offset:1024
	ds_read_b128 v[172:175], v0 offset:2048
	ds_read_b128 v[176:179], v0 offset:3072
	ds_read_b128 v[180:183], v0 offset:4096
	ds_read_b128 v[184:187], v0 offset:5120
	ds_read_b128 v[188:191], v0 offset:6144
	ds_read_b128 v[192:195], v0 offset:7168
	global_load_lds_dwordx4 v[132:133], off
	v_lshl_add_u64 v[130:131], v[130:131], 0, s[10:11]
	s_mov_b32 m0, s0
	s_nop 0
	global_load_lds_dwordx4 v[130:131], off
	s_barrier
	s_waitcnt lgkmcnt(0)
	s_setprio 1
	s_waitcnt lgkmcnt(0)
	v_mfma_f32_16x16x32_bf16 v[126:129], v[134:137], v[164:167], v[126:129]
	v_mfma_f32_16x16x32_bf16 v[122:125], v[152:155], v[164:167], v[122:125]
	v_mfma_f32_16x16x32_bf16 v[114:117], v[152:155], v[172:175], v[114:117]
	v_mfma_f32_16x16x32_bf16 v[106:109], v[152:155], v[180:183], v[106:109]
	v_mfma_f32_16x16x32_bf16 v[98:101], v[152:155], v[188:191], v[98:101]
	v_mfma_f32_16x16x32_bf16 v[126:129], v[138:141], v[168:171], v[126:129]
	v_mfma_f32_16x16x32_bf16 v[122:125], v[156:159], v[168:171], v[122:125]
	v_mfma_f32_16x16x32_bf16 v[118:121], v[134:137], v[172:175], v[118:121]
	v_mfma_f32_16x16x32_bf16 v[114:117], v[156:159], v[176:179], v[114:117]
	v_mfma_f32_16x16x32_bf16 v[110:113], v[134:137], v[180:183], v[110:113]
	v_mfma_f32_16x16x32_bf16 v[106:109], v[156:159], v[184:187], v[106:109]
	v_mfma_f32_16x16x32_bf16 v[102:105], v[134:137], v[188:191], v[102:105]
	v_mfma_f32_16x16x32_bf16 v[98:101], v[156:159], v[192:195], v[98:101]
	v_mfma_f32_16x16x32_bf16 v[130:133], v[138:141], v[176:179], v[118:121]
	v_mfma_f32_16x16x32_bf16 v[160:163], v[138:141], v[184:187], v[110:113]
	v_mfma_f32_16x16x32_bf16 v[196:199], v[138:141], v[192:195], v[102:105]
	s_setprio 0
	s_barrier
	s_nop 0
	ds_read_b128 v[102:105], v151 offset:16384
	ds_read_b128 v[110:113], v151 offset:17408
	ds_read_b128 v[118:121], v151 offset:18432
	ds_read_b128 v[200:203], v151 offset:19456
	s_barrier
	s_waitcnt lgkmcnt(0)
	s_setprio 1
	s_waitcnt lgkmcnt(1)
	v_mfma_f32_16x16x32_bf16 v[90:93], v[118:121], v[164:167], v[90:93]
	v_mfma_f32_16x16x32_bf16 v[86:89], v[102:105], v[172:175], v[86:89]
	v_mfma_f32_16x16x32_bf16 v[82:85], v[118:121], v[172:175], v[82:85]
	v_mfma_f32_16x16x32_bf16 v[78:81], v[102:105], v[180:183], v[78:81]
	v_mfma_f32_16x16x32_bf16 v[70:73], v[102:105], v[188:191], v[70:73]
	v_mfma_f32_16x16x32_bf16 v[94:97], v[102:105], v[164:167], v[94:97]
	s_waitcnt lgkmcnt(0)
	v_mfma_f32_16x16x32_bf16 v[90:93], v[200:203], v[168:171], v[90:93]
	v_mfma_f32_16x16x32_bf16 v[86:89], v[110:113], v[176:179], v[86:89]
	v_mfma_f32_16x16x32_bf16 v[82:85], v[200:203], v[176:179], v[82:85]
	v_mfma_f32_16x16x32_bf16 v[78:81], v[110:113], v[184:187], v[78:81]
	v_mfma_f32_16x16x32_bf16 v[74:77], v[118:121], v[180:183], v[74:77]
	v_mfma_f32_16x16x32_bf16 v[70:73], v[110:113], v[192:195], v[70:73]
	v_mfma_f32_16x16x32_bf16 v[66:69], v[118:121], v[188:191], v[66:69]
	v_mfma_f32_16x16x32_bf16 v[222:225], v[110:113], v[168:171], v[94:97]
	v_mfma_f32_16x16x32_bf16 v[164:167], v[200:203], v[184:187], v[74:77]
	v_mfma_f32_16x16x32_bf16 v[168:171], v[200:203], v[192:195], v[66:69]
	s_setprio 0
	s_barrier
	s_nop 2
	ds_read_b128 v[66:69], v0 offset:16384
	ds_read_b128 v[74:77], v0 offset:17408
	ds_read_b128 v[94:97], v0 offset:18432
	ds_read_b128 v[172:175], v0 offset:19456
	ds_read_b128 v[176:179], v0 offset:20480
	ds_read_b128 v[180:183], v0 offset:21504
	ds_read_b128 v[184:187], v0 offset:22528
	ds_read_b128 v[188:191], v0 offset:23552
	s_waitcnt vmcnt(4)
	s_barrier
	s_waitcnt lgkmcnt(0)
	s_setprio 1
	s_waitcnt lgkmcnt(5)
	v_mfma_f32_16x16x32_bf16 v[54:57], v[134:137], v[94:97], v[54:57]
	v_mfma_f32_16x16x32_bf16 v[50:53], v[152:155], v[94:97], v[50:53]
	v_mfma_f32_16x16x32_bf16 v[62:65], v[134:137], v[66:69], v[62:65]
	v_mfma_f32_16x16x32_bf16 v[58:61], v[152:155], v[66:69], v[58:61]
	s_waitcnt lgkmcnt(4)
	v_mfma_f32_16x16x32_bf16 v[54:57], v[138:141], v[172:175], v[54:57]
	v_mfma_f32_16x16x32_bf16 v[50:53], v[156:159], v[172:175], v[50:53]
	s_waitcnt lgkmcnt(3)
	v_mfma_f32_16x16x32_bf16 v[46:49], v[134:137], v[176:179], v[46:49]
	v_mfma_f32_16x16x32_bf16 v[42:45], v[152:155], v[176:179], v[42:45]
	s_waitcnt lgkmcnt(1)
	v_mfma_f32_16x16x32_bf16 v[38:41], v[134:137], v[184:187], v[38:41]
	v_mfma_f32_16x16x32_bf16 v[34:37], v[152:155], v[184:187], v[34:37]
	v_mfma_f32_16x16x32_bf16 v[192:195], v[138:141], v[74:77], v[62:65]
	v_mfma_f32_16x16x32_bf16 v[232:235], v[156:159], v[74:77], v[58:61]
	v_mfma_f32_16x16x32_bf16 v[236:239], v[138:141], v[180:183], v[46:49]
	v_mfma_f32_16x16x32_bf16 v[240:243], v[156:159], v[180:183], v[42:45]
	s_waitcnt lgkmcnt(0)
	v_mfma_f32_16x16x32_bf16 v[134:137], v[138:141], v[188:191], v[38:41]
	v_mfma_f32_16x16x32_bf16 v[138:141], v[156:159], v[188:191], v[34:37]
	s_setprio 0
	s_setprio 1
	v_mfma_f32_16x16x32_bf16 v[30:33], v[102:105], v[66:69], v[30:33]
	v_mfma_f32_16x16x32_bf16 v[26:29], v[118:121], v[66:69], v[26:29]
	v_mfma_f32_16x16x32_bf16 v[14:17], v[102:105], v[176:179], v[14:17]
	v_mfma_f32_16x16x32_bf16 v[10:13], v[118:121], v[176:179], v[10:13]
	v_mfma_f32_16x16x32_bf16 v[30:33], v[110:113], v[74:77], v[30:33]
	v_mfma_f32_16x16x32_bf16 v[26:29], v[200:203], v[74:77], v[26:29]
	v_mfma_f32_16x16x32_bf16 v[22:25], v[102:105], v[94:97], v[22:25]
	v_mfma_f32_16x16x32_bf16 v[18:21], v[118:121], v[94:97], v[18:21]
	v_mfma_f32_16x16x32_bf16 v[14:17], v[110:113], v[180:183], v[14:17]
	v_mfma_f32_16x16x32_bf16 v[10:13], v[200:203], v[180:183], v[10:13]
	v_mfma_f32_16x16x32_bf16 v[6:9], v[102:105], v[184:187], v[6:9]
	v_mfma_f32_16x16x32_bf16 v[2:5], v[118:121], v[184:187], v[2:5]
	v_mfma_f32_16x16x32_bf16 v[152:155], v[110:113], v[172:175], v[22:25]
	v_mfma_f32_16x16x32_bf16 v[156:159], v[200:203], v[172:175], v[18:21]
	v_mfma_f32_16x16x32_bf16 v[172:175], v[110:113], v[188:191], v[6:9]
	v_mfma_f32_16x16x32_bf16 v[176:179], v[200:203], v[188:191], v[2:5]
	s_setprio 0
	s_barrier
	s_nop 1
	ds_read_b128 v[2:5], v151 offset:32768
	ds_read_b128 v[6:9], v151 offset:33792
	ds_read_b128 v[180:183], v151 offset:34816
	ds_read_b128 v[184:187], v151 offset:35840
	ds_read_b128 v[18:21], v0 offset:32768
	ds_read_b128 v[22:25], v0 offset:33792
	ds_read_b128 v[38:41], v0 offset:34816
	ds_read_b128 v[46:49], v0 offset:35840
	ds_read_b128 v[58:61], v0 offset:36864
	ds_read_b128 v[66:69], v0 offset:37888
	ds_read_b128 v[188:191], v0 offset:38912
	ds_read_b128 v[200:203], v0 offset:39936
	s_waitcnt vmcnt(2)
	s_barrier
	s_waitcnt lgkmcnt(0)
	s_setprio 1
	s_waitcnt lgkmcnt(7)
	v_mfma_f32_16x16x32_bf16 v[34:37], v[2:5], v[18:21], v[126:129]
	s_waitcnt lgkmcnt(6)
	v_mfma_f32_16x16x32_bf16 v[118:121], v[6:9], v[22:25], v[34:37]
	v_mfma_f32_16x16x32_bf16 v[34:37], v[180:183], v[18:21], v[122:125]
	v_mfma_f32_16x16x32_bf16 v[110:113], v[184:187], v[22:25], v[34:37]
	s_waitcnt lgkmcnt(5)
	v_mfma_f32_16x16x32_bf16 v[34:37], v[2:5], v[38:41], v[130:133]
	s_waitcnt lgkmcnt(4)
	v_mfma_f32_16x16x32_bf16 v[102:105], v[6:9], v[46:49], v[34:37]
	v_mfma_f32_16x16x32_bf16 v[34:37], v[180:183], v[38:41], v[114:117]
	v_mfma_f32_16x16x32_bf16 v[94:97], v[184:187], v[46:49], v[34:37]
	s_waitcnt lgkmcnt(3)
	v_mfma_f32_16x16x32_bf16 v[34:37], v[2:5], v[58:61], v[160:163]
	s_waitcnt lgkmcnt(2)
	v_mfma_f32_16x16x32_bf16 v[74:77], v[6:9], v[66:69], v[34:37]
	v_mfma_f32_16x16x32_bf16 v[34:37], v[180:183], v[58:61], v[106:109]
	v_mfma_f32_16x16x32_bf16 v[62:65], v[184:187], v[66:69], v[34:37]
	s_waitcnt lgkmcnt(1)
	v_mfma_f32_16x16x32_bf16 v[34:37], v[2:5], v[188:191], v[196:199]
	s_waitcnt lgkmcnt(0)
	v_mfma_f32_16x16x32_bf16 v[42:45], v[6:9], v[200:203], v[34:37]
	v_mfma_f32_16x16x32_bf16 v[34:37], v[180:183], v[188:191], v[98:101]
	v_mfma_f32_16x16x32_bf16 v[34:37], v[184:187], v[200:203], v[34:37]
	s_setprio 0
	s_barrier
	ds_read_b128 v[130:133], v151 offset:49152
	ds_read_b128 v[160:163], v151 offset:50176
	ds_read_b128 v[196:199], v151 offset:51200
	ds_read_b128 v[148:151], v151 offset:52224
	s_waitcnt vmcnt(0)
	s_barrier
	s_waitcnt lgkmcnt(0)
	s_setprio 1
	s_waitcnt lgkmcnt(3)
	v_mfma_f32_16x16x32_bf16 v[98:101], v[130:133], v[18:21], v[222:225]
	s_waitcnt lgkmcnt(1)
	v_mfma_f32_16x16x32_bf16 v[18:21], v[196:199], v[18:21], v[90:93]
	s_waitcnt lgkmcnt(0)
	v_mfma_f32_16x16x32_bf16 v[122:125], v[148:151], v[22:25], v[18:21]
	v_mfma_f32_16x16x32_bf16 v[18:21], v[130:133], v[38:41], v[86:89]
	v_mfma_f32_16x16x32_bf16 v[114:117], v[160:163], v[46:49], v[18:21]
	v_mfma_f32_16x16x32_bf16 v[18:21], v[196:199], v[38:41], v[82:85]
	v_mfma_f32_16x16x32_bf16 v[106:109], v[148:151], v[46:49], v[18:21]
	v_mfma_f32_16x16x32_bf16 v[18:21], v[130:133], v[58:61], v[78:81]
	v_mfma_f32_16x16x32_bf16 v[126:129], v[160:163], v[22:25], v[98:101]
	v_mfma_f32_16x16x32_bf16 v[98:101], v[160:163], v[66:69], v[18:21]
	v_mfma_f32_16x16x32_bf16 v[18:21], v[196:199], v[58:61], v[164:167]
	v_mfma_f32_16x16x32_bf16 v[90:93], v[148:151], v[66:69], v[18:21]
	v_mfma_f32_16x16x32_bf16 v[18:21], v[130:133], v[188:191], v[70:73]
	v_mfma_f32_16x16x32_bf16 v[66:69], v[160:163], v[200:203], v[18:21]
	v_mfma_f32_16x16x32_bf16 v[18:21], v[196:199], v[188:191], v[168:171]
	v_mfma_f32_16x16x32_bf16 v[58:61], v[148:151], v[200:203], v[18:21]
	s_setprio 0
	s_barrier
	ds_read_b128 v[82:85], v0 offset:49152
	ds_read_b128 v[164:167], v0 offset:50176
	ds_read_b128 v[168:171], v0 offset:51200
	ds_read_b128 v[188:191], v0 offset:52224
	ds_read_b128 v[200:203], v0 offset:53248
	ds_read_b128 v[222:225], v0 offset:54272
	ds_read_b128 v[244:247], v0 offset:55296
	ds_read_b128 v[248:251], v0 offset:56320
	s_barrier
	s_waitcnt lgkmcnt(0)
	s_setprio 1
	s_waitcnt lgkmcnt(7)
	v_mfma_f32_16x16x32_bf16 v[18:21], v[2:5], v[82:85], v[192:195]
	s_waitcnt lgkmcnt(6)
	v_mfma_f32_16x16x32_bf16 v[78:81], v[6:9], v[164:167], v[18:21]
	v_mfma_f32_16x16x32_bf16 v[18:21], v[180:183], v[82:85], v[232:235]
	v_mfma_f32_16x16x32_bf16 v[70:73], v[184:187], v[164:167], v[18:21]
	s_waitcnt lgkmcnt(5)
	v_mfma_f32_16x16x32_bf16 v[18:21], v[2:5], v[168:171], v[54:57]
	s_waitcnt lgkmcnt(4)
	v_mfma_f32_16x16x32_bf16 v[46:49], v[6:9], v[188:191], v[18:21]
	v_mfma_f32_16x16x32_bf16 v[18:21], v[180:183], v[168:171], v[50:53]
	v_mfma_f32_16x16x32_bf16 v[38:41], v[184:187], v[188:191], v[18:21]
	s_waitcnt lgkmcnt(3)
	v_mfma_f32_16x16x32_bf16 v[18:21], v[2:5], v[200:203], v[236:239]
	s_waitcnt lgkmcnt(1)
	v_mfma_f32_16x16x32_bf16 v[2:5], v[2:5], v[244:247], v[134:137]
	v_mfma_f32_16x16x32_bf16 v[22:25], v[6:9], v[222:225], v[18:21]
	v_mfma_f32_16x16x32_bf16 v[18:21], v[180:183], v[200:203], v[240:243]
	s_waitcnt lgkmcnt(0)
	v_mfma_f32_16x16x32_bf16 v[6:9], v[6:9], v[248:251], v[2:5]
	v_mfma_f32_16x16x32_bf16 v[2:5], v[180:183], v[244:247], v[138:141]
	v_mfma_f32_16x16x32_bf16 v[18:21], v[184:187], v[222:225], v[18:21]
	v_mfma_f32_16x16x32_bf16 v[2:5], v[184:187], v[248:251], v[2:5]
	s_setprio 0
	s_setprio 1
	v_mfma_f32_16x16x32_bf16 v[26:29], v[196:199], v[82:85], v[26:29]
	v_mfma_f32_16x16x32_bf16 v[30:33], v[130:133], v[82:85], v[30:33]
	v_mfma_f32_16x16x32_bf16 v[82:85], v[148:151], v[164:167], v[26:29]
	v_mfma_f32_16x16x32_bf16 v[26:29], v[130:133], v[168:171], v[152:155]
	v_mfma_f32_16x16x32_bf16 v[54:57], v[160:163], v[188:191], v[26:29]
	v_mfma_f32_16x16x32_bf16 v[26:29], v[196:199], v[168:171], v[156:159]
	v_mfma_f32_16x16x32_bf16 v[10:13], v[196:199], v[200:203], v[10:13]
	v_mfma_f32_16x16x32_bf16 v[50:53], v[148:151], v[188:191], v[26:29]
	v_mfma_f32_16x16x32_bf16 v[14:17], v[130:133], v[200:203], v[14:17]
	v_mfma_f32_16x16x32_bf16 v[26:29], v[148:151], v[222:225], v[10:13]
	v_mfma_f32_16x16x32_bf16 v[10:13], v[130:133], v[244:247], v[172:175]
	v_mfma_f32_16x16x32_bf16 v[86:89], v[160:163], v[164:167], v[30:33]
	v_mfma_f32_16x16x32_bf16 v[30:33], v[160:163], v[222:225], v[14:17]
	v_mfma_f32_16x16x32_bf16 v[14:17], v[160:163], v[248:251], v[10:13]
	v_mfma_f32_16x16x32_bf16 v[10:13], v[196:199], v[244:247], v[176:179]
	v_mfma_f32_16x16x32_bf16 v[10:13], v[148:151], v[248:251], v[10:13]
	s_setprio 0
	s_movk_i32 s0, 0x100
	v_cmp_gt_u32_e32 vcc, s0, v142
	s_barrier
	s_and_saveexec_b64 s[0:1], vcc
	s_cbranch_execz .LBB0_81
	s_barrier
	s_branch .LBB0_81

.LBB0_180:
	ds_read_b128 v[164:167], v151
	ds_read_b128 v[168:171], v151 offset:1024
	ds_read_b128 v[172:175], v151 offset:2048
	ds_read_b128 v[176:179], v151 offset:3072
	v_lshl_add_u64 v[204:205], v[138:139], 0, s[12:13]
	v_lshl_add_u64 v[228:229], v[204:205], 0, s[60:61]
	s_add_i32 m0, s1, 0xc000
	ds_read_b128 v[180:183], v0
	ds_read_b128 v[184:187], v0 offset:1024
	ds_read_b128 v[188:191], v0 offset:2048
	ds_read_b128 v[192:195], v0 offset:3072
	ds_read_b128 v[196:199], v0 offset:4096
	ds_read_b128 v[200:203], v0 offset:5120
	ds_read_b128 v[222:225], v0 offset:6144
	ds_read_b128 v[232:235], v0 offset:7168
	global_load_lds_dwordx4 v[228:229], off
	v_lshl_add_u64 v[210:211], v[140:141], 0, s[12:13]
	s_add_i32 m0, s1, 0xe000
	v_lshl_add_u64 v[152:153], v[210:211], 0, s[60:61]
	global_load_lds_dwordx4 v[152:153], off
	s_waitcnt lgkmcnt(8)
	s_barrier
	s_waitcnt lgkmcnt(0)
	v_mfma_f32_16x16x32_bf16 v[126:129], v[164:167], v[180:183], v[126:129]
	v_mfma_f32_16x16x32_bf16 v[122:125], v[172:175], v[180:183], v[122:125]
	v_mfma_f32_16x16x32_bf16 v[118:121], v[164:167], v[188:191], v[118:121]
	ds_read_b128 v[236:239], v151 offset:16384
	v_mfma_f32_16x16x32_bf16 v[114:117], v[172:175], v[188:191], v[114:117]
	v_mfma_f32_16x16x32_bf16 v[110:113], v[164:167], v[196:199], v[110:113]
	v_mfma_f32_16x16x32_bf16 v[106:109], v[172:175], v[196:199], v[106:109]
	ds_read_b128 v[240:243], v151 offset:17408
	v_mfma_f32_16x16x32_bf16 v[102:105], v[164:167], v[222:225], v[102:105]
	v_mfma_f32_16x16x32_bf16 v[98:101], v[172:175], v[222:225], v[98:101]
	v_mfma_f32_16x16x32_bf16 v[126:129], v[168:171], v[184:187], v[126:129]
	ds_read_b128 v[244:247], v151 offset:18432
	v_mfma_f32_16x16x32_bf16 v[122:125], v[176:179], v[184:187], v[122:125]
	v_mfma_f32_16x16x32_bf16 v[118:121], v[168:171], v[192:195], v[118:121]
	v_mfma_f32_16x16x32_bf16 v[114:117], v[176:179], v[192:195], v[114:117]
	ds_read_b128 v[248:251], v151 offset:19456
	v_mfma_f32_16x16x32_bf16 v[110:113], v[168:171], v[200:203], v[110:113]
	v_mfma_f32_16x16x32_bf16 v[106:109], v[176:179], v[200:203], v[106:109]
	v_mfma_f32_16x16x32_bf16 v[102:105], v[168:171], v[232:235], v[102:105]
	v_mfma_f32_16x16x32_bf16 v[98:101], v[176:179], v[232:235], v[98:101]
	s_barrier
	v_lshl_add_u64 v[216:217], v[134:135], 0, s[12:13]
	s_add_i32 m0, s1, 0xff00
	global_load_lds_dwordx4 v[216:217], off offset:256
	s_add_i32 m0, s1, 0x11f00
	v_lshl_add_u64 v[218:219], v[136:137], 0, s[12:13]
	global_load_lds_dwordx4 v[218:219], off offset:256
	s_barrier
	s_waitcnt lgkmcnt(0)
	v_mfma_f32_16x16x32_bf16 v[94:97], v[236:239], v[180:183], v[94:97]
	v_mfma_f32_16x16x32_bf16 v[90:93], v[244:247], v[180:183], v[90:93]
	v_mfma_f32_16x16x32_bf16 v[86:89], v[236:239], v[188:191], v[86:89]
	v_mfma_f32_16x16x32_bf16 v[82:85], v[244:247], v[188:191], v[82:85]
	v_mfma_f32_16x16x32_bf16 v[78:81], v[236:239], v[196:199], v[78:81]
	v_mfma_f32_16x16x32_bf16 v[74:77], v[244:247], v[196:199], v[74:77]
	v_mfma_f32_16x16x32_bf16 v[70:73], v[236:239], v[222:225], v[70:73]
	v_mfma_f32_16x16x32_bf16 v[66:69], v[244:247], v[222:225], v[66:69]
	v_mfma_f32_16x16x32_bf16 v[94:97], v[240:243], v[184:187], v[94:97]
	v_mfma_f32_16x16x32_bf16 v[90:93], v[248:251], v[184:187], v[90:93]
	v_mfma_f32_16x16x32_bf16 v[86:89], v[240:243], v[192:195], v[86:89]
	v_mfma_f32_16x16x32_bf16 v[82:85], v[248:251], v[192:195], v[82:85]
	v_mfma_f32_16x16x32_bf16 v[78:81], v[240:243], v[200:203], v[78:81]
	v_mfma_f32_16x16x32_bf16 v[74:77], v[248:251], v[200:203], v[74:77]
	v_mfma_f32_16x16x32_bf16 v[70:73], v[240:243], v[232:235], v[70:73]
	v_mfma_f32_16x16x32_bf16 v[66:69], v[248:251], v[232:235], v[66:69]
	v_lshl_add_u64 v[158:159], v[204:205], 0, s[74:75]
	s_mov_b32 m0, s1
	s_barrier
	ds_read_b128 v[180:183], v0 offset:16384
	ds_read_b128 v[184:187], v0 offset:17408
	ds_read_b128 v[188:191], v0 offset:18432
	ds_read_b128 v[192:195], v0 offset:19456
	ds_read_b128 v[196:199], v0 offset:20480
	ds_read_b128 v[200:203], v0 offset:21504
	ds_read_b128 v[222:225], v0 offset:22528
	ds_read_b128 v[232:235], v0 offset:23552
	global_load_lds_dwordx4 v[158:159], off
	s_add_i32 m0, s1, 0x1f00
	s_nop 0
	global_load_lds_dwordx4 v[210:211], off offset:256
	s_barrier
	s_waitcnt lgkmcnt(0)
	v_mfma_f32_16x16x32_bf16 v[62:65], v[164:167], v[180:183], v[62:65]
	v_mfma_f32_16x16x32_bf16 v[58:61], v[172:175], v[180:183], v[58:61]
	v_mfma_f32_16x16x32_bf16 v[54:57], v[164:167], v[188:191], v[54:57]
	v_mfma_f32_16x16x32_bf16 v[50:53], v[172:175], v[188:191], v[50:53]
	v_mfma_f32_16x16x32_bf16 v[46:49], v[164:167], v[196:199], v[46:49]
	v_mfma_f32_16x16x32_bf16 v[42:45], v[172:175], v[196:199], v[42:45]
	v_mfma_f32_16x16x32_bf16 v[38:41], v[164:167], v[222:225], v[38:41]
	v_mfma_f32_16x16x32_bf16 v[34:37], v[172:175], v[222:225], v[34:37]
	v_mfma_f32_16x16x32_bf16 v[62:65], v[168:171], v[184:187], v[62:65]
	v_mfma_f32_16x16x32_bf16 v[58:61], v[176:179], v[184:187], v[58:61]
	v_mfma_f32_16x16x32_bf16 v[54:57], v[168:171], v[192:195], v[54:57]
	v_mfma_f32_16x16x32_bf16 v[50:53], v[176:179], v[192:195], v[50:53]
	v_mfma_f32_16x16x32_bf16 v[46:49], v[168:171], v[200:203], v[46:49]
	v_mfma_f32_16x16x32_bf16 v[42:45], v[176:179], v[200:203], v[42:45]
	v_mfma_f32_16x16x32_bf16 v[38:41], v[168:171], v[232:235], v[38:41]
	v_mfma_f32_16x16x32_bf16 v[34:37], v[176:179], v[232:235], v[34:37]
	s_barrier
	s_add_i32 m0, s1, 0x14000
	v_lshl_add_u64 v[154:155], v[216:217], 0, s[18:19]
	global_load_lds_dwordx4 v[154:155], off
	s_add_i32 m0, s1, 0x16000
	v_lshl_add_u64 v[156:157], v[218:219], 0, s[18:19]
	global_load_lds_dwordx4 v[156:157], off
	s_waitcnt vmcnt(6)
	s_barrier
	v_mfma_f32_16x16x32_bf16 v[30:33], v[236:239], v[180:183], v[30:33]
	v_mfma_f32_16x16x32_bf16 v[26:29], v[244:247], v[180:183], v[26:29]
	v_mfma_f32_16x16x32_bf16 v[22:25], v[236:239], v[188:191], v[22:25]
	ds_read_b128 v[164:167], v151 offset:32768
	v_mfma_f32_16x16x32_bf16 v[18:21], v[244:247], v[188:191], v[18:21]
	v_mfma_f32_16x16x32_bf16 v[14:17], v[236:239], v[196:199], v[14:17]
	v_mfma_f32_16x16x32_bf16 v[10:13], v[244:247], v[196:199], v[10:13]
	ds_read_b128 v[168:171], v151 offset:33792
	v_mfma_f32_16x16x32_bf16 v[6:9], v[236:239], v[222:225], v[6:9]
	v_mfma_f32_16x16x32_bf16 v[2:5], v[244:247], v[222:225], v[2:5]
	v_mfma_f32_16x16x32_bf16 v[30:33], v[240:243], v[184:187], v[30:33]
	ds_read_b128 v[172:175], v151 offset:34816
	v_mfma_f32_16x16x32_bf16 v[26:29], v[248:251], v[184:187], v[26:29]
	v_mfma_f32_16x16x32_bf16 v[22:25], v[240:243], v[192:195], v[22:25]
	v_mfma_f32_16x16x32_bf16 v[18:21], v[248:251], v[192:195], v[18:21]
	ds_read_b128 v[176:179], v151 offset:35840
	v_mfma_f32_16x16x32_bf16 v[14:17], v[240:243], v[200:203], v[14:17]
	v_mfma_f32_16x16x32_bf16 v[10:13], v[248:251], v[200:203], v[10:13]
	v_mfma_f32_16x16x32_bf16 v[6:9], v[240:243], v[232:235], v[6:9]
	v_mfma_f32_16x16x32_bf16 v[2:5], v[248:251], v[232:235], v[2:5]
	s_barrier
	s_add_i32 m0, s1, 0x3f80
	ds_read_b128 v[180:183], v0 offset:32768
	ds_read_b128 v[184:187], v0 offset:33792
	ds_read_b128 v[188:191], v0 offset:34816
	ds_read_b128 v[192:195], v0 offset:35840
	ds_read_b128 v[196:199], v0 offset:36864
	ds_read_b128 v[200:203], v0 offset:37888
	ds_read_b128 v[222:225], v0 offset:38912
	ds_read_b128 v[232:235], v0 offset:39936
	global_load_lds_dwordx4 v[228:229], off offset:128
	s_add_i32 m0, s1, 0x5f80
	s_nop 0
	global_load_lds_dwordx4 v[152:153], off offset:128
	s_waitcnt lgkmcnt(8)
	s_barrier
	s_waitcnt lgkmcnt(0)
	v_mfma_f32_16x16x32_bf16 v[126:129], v[164:167], v[180:183], v[126:129]
	v_mfma_f32_16x16x32_bf16 v[122:125], v[172:175], v[180:183], v[122:125]
	v_mfma_f32_16x16x32_bf16 v[118:121], v[164:167], v[188:191], v[118:121]
	ds_read_b128 v[236:239], v151 offset:49152
	v_mfma_f32_16x16x32_bf16 v[114:117], v[172:175], v[188:191], v[114:117]
	v_mfma_f32_16x16x32_bf16 v[110:113], v[164:167], v[196:199], v[110:113]
	v_mfma_f32_16x16x32_bf16 v[106:109], v[172:175], v[196:199], v[106:109]
	ds_read_b128 v[240:243], v151 offset:50176
	v_mfma_f32_16x16x32_bf16 v[102:105], v[164:167], v[222:225], v[102:105]
	v_mfma_f32_16x16x32_bf16 v[98:101], v[172:175], v[222:225], v[98:101]
	v_mfma_f32_16x16x32_bf16 v[126:129], v[168:171], v[184:187], v[126:129]
	ds_read_b128 v[244:247], v151 offset:51200
	v_mfma_f32_16x16x32_bf16 v[122:125], v[176:179], v[184:187], v[122:125]
	v_mfma_f32_16x16x32_bf16 v[118:121], v[168:171], v[192:195], v[118:121]
	v_mfma_f32_16x16x32_bf16 v[114:117], v[176:179], v[192:195], v[114:117]
	ds_read_b128 v[248:251], v151 offset:52224
	v_mfma_f32_16x16x32_bf16 v[110:113], v[168:171], v[200:203], v[110:113]
	v_mfma_f32_16x16x32_bf16 v[106:109], v[176:179], v[200:203], v[106:109]
	v_mfma_f32_16x16x32_bf16 v[102:105], v[168:171], v[232:235], v[102:105]
	v_mfma_f32_16x16x32_bf16 v[98:101], v[176:179], v[232:235], v[98:101]
	s_barrier
	s_add_i32 m0, s1, 0x17e80
	global_load_lds_dwordx4 v[216:217], off offset:384
	s_add_i32 m0, s1, 0x19e80
	s_nop 0
	global_load_lds_dwordx4 v[218:219], off offset:384
	s_barrier
	s_waitcnt lgkmcnt(0)
	v_mfma_f32_16x16x32_bf16 v[94:97], v[236:239], v[180:183], v[94:97]
	v_mfma_f32_16x16x32_bf16 v[90:93], v[244:247], v[180:183], v[90:93]
	v_mfma_f32_16x16x32_bf16 v[86:89], v[236:239], v[188:191], v[86:89]
	v_mfma_f32_16x16x32_bf16 v[82:85], v[244:247], v[188:191], v[82:85]
	v_mfma_f32_16x16x32_bf16 v[78:81], v[236:239], v[196:199], v[78:81]
	v_mfma_f32_16x16x32_bf16 v[74:77], v[244:247], v[196:199], v[74:77]
	v_mfma_f32_16x16x32_bf16 v[70:73], v[236:239], v[222:225], v[70:73]
	v_mfma_f32_16x16x32_bf16 v[66:69], v[244:247], v[222:225], v[66:69]
	v_mfma_f32_16x16x32_bf16 v[94:97], v[240:243], v[184:187], v[94:97]
	v_mfma_f32_16x16x32_bf16 v[90:93], v[248:251], v[184:187], v[90:93]
	v_mfma_f32_16x16x32_bf16 v[86:89], v[240:243], v[192:195], v[86:89]
	v_mfma_f32_16x16x32_bf16 v[82:85], v[248:251], v[192:195], v[82:85]
	v_mfma_f32_16x16x32_bf16 v[78:81], v[240:243], v[200:203], v[78:81]
	v_mfma_f32_16x16x32_bf16 v[74:77], v[248:251], v[200:203], v[74:77]
	v_mfma_f32_16x16x32_bf16 v[70:73], v[240:243], v[232:235], v[70:73]
	v_mfma_f32_16x16x32_bf16 v[66:69], v[248:251], v[232:235], v[66:69]
	s_add_i32 m0, s1, 0x7e80
	s_barrier
	ds_read_b128 v[180:183], v0 offset:49152
	ds_read_b128 v[184:187], v0 offset:50176
	ds_read_b128 v[188:191], v0 offset:51200
	ds_read_b128 v[192:195], v0 offset:52224
	ds_read_b128 v[196:199], v0 offset:53248
	ds_read_b128 v[200:203], v0 offset:54272
	ds_read_b128 v[222:225], v0 offset:55296
	ds_read_b128 v[232:235], v0 offset:56320
	global_load_lds_dwordx4 v[204:205], off offset:384
	s_add_i32 m0, s1, 0x9e80
	s_nop 0
	global_load_lds_dwordx4 v[210:211], off offset:384
	s_barrier
	s_waitcnt lgkmcnt(0)
	v_mfma_f32_16x16x32_bf16 v[62:65], v[164:167], v[180:183], v[62:65]
	v_mfma_f32_16x16x32_bf16 v[58:61], v[172:175], v[180:183], v[58:61]
	v_mfma_f32_16x16x32_bf16 v[54:57], v[164:167], v[188:191], v[54:57]
	v_mfma_f32_16x16x32_bf16 v[50:53], v[172:175], v[188:191], v[50:53]
	v_mfma_f32_16x16x32_bf16 v[46:49], v[164:167], v[196:199], v[46:49]
	v_mfma_f32_16x16x32_bf16 v[42:45], v[172:175], v[196:199], v[42:45]
	v_mfma_f32_16x16x32_bf16 v[38:41], v[164:167], v[222:225], v[38:41]
	v_mfma_f32_16x16x32_bf16 v[34:37], v[172:175], v[222:225], v[34:37]
	v_mfma_f32_16x16x32_bf16 v[62:65], v[168:171], v[184:187], v[62:65]
	v_mfma_f32_16x16x32_bf16 v[58:61], v[176:179], v[184:187], v[58:61]
	v_mfma_f32_16x16x32_bf16 v[54:57], v[168:171], v[192:195], v[54:57]
	v_mfma_f32_16x16x32_bf16 v[50:53], v[176:179], v[192:195], v[50:53]
	v_mfma_f32_16x16x32_bf16 v[46:49], v[168:171], v[200:203], v[46:49]
	v_mfma_f32_16x16x32_bf16 v[42:45], v[176:179], v[200:203], v[42:45]
	v_mfma_f32_16x16x32_bf16 v[38:41], v[168:171], v[232:235], v[38:41]
	v_mfma_f32_16x16x32_bf16 v[34:37], v[176:179], v[232:235], v[34:37]
	s_barrier
	s_add_i32 m0, s1, 0x1bf80
	s_nop 0
	global_load_lds_dwordx4 v[154:155], off offset:128
	s_add_i32 m0, s1, 0x1df80
	s_nop 0
	global_load_lds_dwordx4 v[156:157], off offset:128
	s_waitcnt vmcnt(6)
	s_barrier
	v_mfma_f32_16x16x32_bf16 v[30:33], v[236:239], v[180:183], v[30:33]
	v_mfma_f32_16x16x32_bf16 v[26:29], v[244:247], v[180:183], v[26:29]
	v_mfma_f32_16x16x32_bf16 v[22:25], v[236:239], v[188:191], v[22:25]
	v_mfma_f32_16x16x32_bf16 v[18:21], v[244:247], v[188:191], v[18:21]
	v_mfma_f32_16x16x32_bf16 v[14:17], v[236:239], v[196:199], v[14:17]
	v_mfma_f32_16x16x32_bf16 v[10:13], v[244:247], v[196:199], v[10:13]
	v_mfma_f32_16x16x32_bf16 v[6:9], v[236:239], v[222:225], v[6:9]
	v_mfma_f32_16x16x32_bf16 v[2:5], v[244:247], v[222:225], v[2:5]
	v_mfma_f32_16x16x32_bf16 v[30:33], v[240:243], v[184:187], v[30:33]
	v_mfma_f32_16x16x32_bf16 v[26:29], v[248:251], v[184:187], v[26:29]
	v_mfma_f32_16x16x32_bf16 v[22:25], v[240:243], v[192:195], v[22:25]
	v_mfma_f32_16x16x32_bf16 v[18:21], v[248:251], v[192:195], v[18:21]
	v_mfma_f32_16x16x32_bf16 v[14:17], v[240:243], v[200:203], v[14:17]
	v_mfma_f32_16x16x32_bf16 v[10:13], v[248:251], v[200:203], v[10:13]
	v_mfma_f32_16x16x32_bf16 v[6:9], v[240:243], v[232:235], v[6:9]
	v_mfma_f32_16x16x32_bf16 v[2:5], v[248:251], v[232:235], v[2:5]
	s_add_i32 s0, s0, 2
	s_add_u32 s12, s12, 0x100
	s_addc_u32 s13, s13, 0
	s_cmp_lt_u32 s0, 28
	s_barrier
	s_cbranch_scc1 .LBB0_180
	s_add_i32 s1, s1, 0x1e000
	s_mov_b64 s[12:13], 0xf80
	v_readfirstlane_b32 s0, v162
	v_lshl_add_u64 v[132:133], v[132:133], 0, s[12:13]
	s_mov_b32 m0, s0
	v_readfirstlane_b32 s0, v163
	ds_read_b128 v[134:137], v151
	ds_read_b128 v[138:141], v151 offset:1024
	ds_read_b128 v[152:155], v151 offset:2048
	ds_read_b128 v[156:159], v151 offset:3072
	ds_read_b128 v[164:167], v0
	ds_read_b128 v[168:171], v0 offset:1024
	ds_read_b128 v[172:175], v0 offset:2048
	ds_read_b128 v[176:179], v0 offset:3072
	ds_read_b128 v[180:183], v0 offset:4096
	ds_read_b128 v[184:187], v0 offset:5120
	ds_read_b128 v[188:191], v0 offset:6144
	ds_read_b128 v[192:195], v0 offset:7168
	global_load_lds_dwordx4 v[132:133], off
	v_lshl_add_u64 v[130:131], v[130:131], 0, s[12:13]
	s_mov_b32 m0, s0
	s_nop 0
	global_load_lds_dwordx4 v[130:131], off
	s_barrier
	s_waitcnt lgkmcnt(0)
	s_setprio 1
	s_waitcnt lgkmcnt(0)
	v_mfma_f32_16x16x32_bf16 v[126:129], v[134:137], v[164:167], v[126:129]
	v_mfma_f32_16x16x32_bf16 v[122:125], v[152:155], v[164:167], v[122:125]
	v_mfma_f32_16x16x32_bf16 v[114:117], v[152:155], v[172:175], v[114:117]
	v_mfma_f32_16x16x32_bf16 v[106:109], v[152:155], v[180:183], v[106:109]
	v_mfma_f32_16x16x32_bf16 v[98:101], v[152:155], v[188:191], v[98:101]
	v_mfma_f32_16x16x32_bf16 v[126:129], v[138:141], v[168:171], v[126:129]
	v_mfma_f32_16x16x32_bf16 v[122:125], v[156:159], v[168:171], v[122:125]
	v_mfma_f32_16x16x32_bf16 v[118:121], v[134:137], v[172:175], v[118:121]
	v_mfma_f32_16x16x32_bf16 v[114:117], v[156:159], v[176:179], v[114:117]
	v_mfma_f32_16x16x32_bf16 v[110:113], v[134:137], v[180:183], v[110:113]
	v_mfma_f32_16x16x32_bf16 v[106:109], v[156:159], v[184:187], v[106:109]
	v_mfma_f32_16x16x32_bf16 v[102:105], v[134:137], v[188:191], v[102:105]
	v_mfma_f32_16x16x32_bf16 v[98:101], v[156:159], v[192:195], v[98:101]
	v_mfma_f32_16x16x32_bf16 v[130:133], v[138:141], v[176:179], v[118:121]
	v_mfma_f32_16x16x32_bf16 v[160:163], v[138:141], v[184:187], v[110:113]
	v_mfma_f32_16x16x32_bf16 v[196:199], v[138:141], v[192:195], v[102:105]
	s_setprio 0
	s_barrier
	s_nop 0
	ds_read_b128 v[102:105], v151 offset:16384
	ds_read_b128 v[110:113], v151 offset:17408
	ds_read_b128 v[118:121], v151 offset:18432
	ds_read_b128 v[200:203], v151 offset:19456
	s_barrier
	s_waitcnt lgkmcnt(0)
	s_setprio 1
	s_waitcnt lgkmcnt(1)
	v_mfma_f32_16x16x32_bf16 v[90:93], v[118:121], v[164:167], v[90:93]
	v_mfma_f32_16x16x32_bf16 v[82:85], v[118:121], v[172:175], v[82:85]
	v_mfma_f32_16x16x32_bf16 v[74:77], v[118:121], v[180:183], v[74:77]
	v_mfma_f32_16x16x32_bf16 v[66:69], v[118:121], v[188:191], v[66:69]
	v_mfma_f32_16x16x32_bf16 v[94:97], v[102:105], v[164:167], v[94:97]
	s_waitcnt lgkmcnt(0)
	v_mfma_f32_16x16x32_bf16 v[90:93], v[200:203], v[168:171], v[90:93]
	v_mfma_f32_16x16x32_bf16 v[86:89], v[102:105], v[172:175], v[86:89]
	v_mfma_f32_16x16x32_bf16 v[82:85], v[200:203], v[176:179], v[82:85]
	v_mfma_f32_16x16x32_bf16 v[78:81], v[102:105], v[180:183], v[78:81]
	v_mfma_f32_16x16x32_bf16 v[74:77], v[200:203], v[184:187], v[74:77]
	v_mfma_f32_16x16x32_bf16 v[70:73], v[102:105], v[188:191], v[70:73]
	v_mfma_f32_16x16x32_bf16 v[66:69], v[200:203], v[192:195], v[66:69]
	v_mfma_f32_16x16x32_bf16 v[222:225], v[110:113], v[168:171], v[94:97]
	v_mfma_f32_16x16x32_bf16 v[164:167], v[110:113], v[176:179], v[86:89]
	v_mfma_f32_16x16x32_bf16 v[168:171], v[110:113], v[184:187], v[78:81]
	v_mfma_f32_16x16x32_bf16 v[172:175], v[110:113], v[192:195], v[70:73]
	s_setprio 0
	s_barrier
	s_nop 0
	ds_read_b128 v[70:73], v0 offset:16384
	ds_read_b128 v[78:81], v0 offset:17408
	ds_read_b128 v[86:89], v0 offset:18432
	ds_read_b128 v[94:97], v0 offset:19456
	ds_read_b128 v[176:179], v0 offset:20480
	ds_read_b128 v[180:183], v0 offset:21504
	ds_read_b128 v[184:187], v0 offset:22528
	ds_read_b128 v[188:191], v0 offset:23552
	s_waitcnt vmcnt(4)
	s_barrier
	s_waitcnt lgkmcnt(0)
	s_setprio 1
	s_waitcnt lgkmcnt(7)
	v_mfma_f32_16x16x32_bf16 v[62:65], v[134:137], v[70:73], v[62:65]
	v_mfma_f32_16x16x32_bf16 v[58:61], v[152:155], v[70:73], v[58:61]
	s_waitcnt lgkmcnt(5)
	v_mfma_f32_16x16x32_bf16 v[50:53], v[152:155], v[86:89], v[50:53]
	s_waitcnt lgkmcnt(3)
	v_mfma_f32_16x16x32_bf16 v[42:45], v[152:155], v[176:179], v[42:45]
	s_waitcnt lgkmcnt(1)
	v_mfma_f32_16x16x32_bf16 v[34:37], v[152:155], v[184:187], v[34:37]
	v_mfma_f32_16x16x32_bf16 v[62:65], v[138:141], v[78:81], v[62:65]
	v_mfma_f32_16x16x32_bf16 v[58:61], v[156:159], v[78:81], v[58:61]
	v_mfma_f32_16x16x32_bf16 v[54:57], v[134:137], v[86:89], v[54:57]
	v_mfma_f32_16x16x32_bf16 v[50:53], v[156:159], v[94:97], v[50:53]
	v_mfma_f32_16x16x32_bf16 v[46:49], v[134:137], v[176:179], v[46:49]
	v_mfma_f32_16x16x32_bf16 v[42:45], v[156:159], v[180:183], v[42:45]
	v_mfma_f32_16x16x32_bf16 v[38:41], v[134:137], v[184:187], v[38:41]
	s_waitcnt lgkmcnt(0)
	v_mfma_f32_16x16x32_bf16 v[34:37], v[156:159], v[188:191], v[34:37]
	v_mfma_f32_16x16x32_bf16 v[192:195], v[138:141], v[94:97], v[54:57]
	v_mfma_f32_16x16x32_bf16 v[232:235], v[138:141], v[180:183], v[46:49]
	v_mfma_f32_16x16x32_bf16 v[134:137], v[138:141], v[188:191], v[38:41]
	s_setprio 0
	s_setprio 1
	v_mfma_f32_16x16x32_bf16 v[26:29], v[118:121], v[70:73], v[26:29]
	v_mfma_f32_16x16x32_bf16 v[18:21], v[118:121], v[86:89], v[18:21]
	v_mfma_f32_16x16x32_bf16 v[10:13], v[118:121], v[176:179], v[10:13]
	v_mfma_f32_16x16x32_bf16 v[2:5], v[118:121], v[184:187], v[2:5]
	v_mfma_f32_16x16x32_bf16 v[30:33], v[102:105], v[70:73], v[30:33]
	v_mfma_f32_16x16x32_bf16 v[26:29], v[200:203], v[78:81], v[26:29]
	v_mfma_f32_16x16x32_bf16 v[22:25], v[102:105], v[86:89], v[22:25]
	v_mfma_f32_16x16x32_bf16 v[18:21], v[200:203], v[94:97], v[18:21]
	v_mfma_f32_16x16x32_bf16 v[14:17], v[102:105], v[176:179], v[14:17]
	v_mfma_f32_16x16x32_bf16 v[10:13], v[200:203], v[180:183], v[10:13]
	v_mfma_f32_16x16x32_bf16 v[6:9], v[102:105], v[184:187], v[6:9]
	v_mfma_f32_16x16x32_bf16 v[2:5], v[200:203], v[188:191], v[2:5]
	v_mfma_f32_16x16x32_bf16 v[138:141], v[110:113], v[78:81], v[30:33]
	v_mfma_f32_16x16x32_bf16 v[152:155], v[110:113], v[94:97], v[22:25]
	v_mfma_f32_16x16x32_bf16 v[156:159], v[110:113], v[180:183], v[14:17]
	v_mfma_f32_16x16x32_bf16 v[176:179], v[110:113], v[188:191], v[6:9]
	s_setprio 0
	s_barrier
	s_nop 0
	ds_read_b128 v[6:9], v151 offset:32768
	ds_read_b128 v[14:17], v151 offset:33792
	ds_read_b128 v[180:183], v151 offset:34816
	ds_read_b128 v[184:187], v151 offset:35840
	ds_read_b128 v[22:25], v0 offset:32768
	ds_read_b128 v[30:33], v0 offset:33792
	ds_read_b128 v[38:41], v0 offset:34816
	ds_read_b128 v[46:49], v0 offset:35840
	ds_read_b128 v[54:57], v0 offset:36864
	ds_read_b128 v[188:191], v0 offset:37888
	ds_read_b128 v[200:203], v0 offset:38912
	ds_read_b128 v[236:239], v0 offset:39936
	s_waitcnt vmcnt(2)
	s_barrier
	s_waitcnt lgkmcnt(0)
	s_setprio 1
	s_waitcnt lgkmcnt(7)
	v_mfma_f32_16x16x32_bf16 v[70:73], v[6:9], v[22:25], v[126:129]
	s_waitcnt lgkmcnt(6)
	v_mfma_f32_16x16x32_bf16 v[126:129], v[14:17], v[30:33], v[70:73]
	v_mfma_f32_16x16x32_bf16 v[70:73], v[180:183], v[22:25], v[122:125]
	v_mfma_f32_16x16x32_bf16 v[118:121], v[184:187], v[30:33], v[70:73]
	s_waitcnt lgkmcnt(5)
	v_mfma_f32_16x16x32_bf16 v[70:73], v[6:9], v[38:41], v[130:133]
	s_waitcnt lgkmcnt(4)
	v_mfma_f32_16x16x32_bf16 v[110:113], v[14:17], v[46:49], v[70:73]
	v_mfma_f32_16x16x32_bf16 v[70:73], v[180:183], v[38:41], v[114:117]
	v_mfma_f32_16x16x32_bf16 v[102:105], v[184:187], v[46:49], v[70:73]
	s_waitcnt lgkmcnt(3)
	v_mfma_f32_16x16x32_bf16 v[70:73], v[6:9], v[54:57], v[160:163]
	s_waitcnt lgkmcnt(2)
	v_mfma_f32_16x16x32_bf16 v[94:97], v[14:17], v[188:191], v[70:73]
	v_mfma_f32_16x16x32_bf16 v[70:73], v[180:183], v[54:57], v[106:109]
	v_mfma_f32_16x16x32_bf16 v[86:89], v[184:187], v[188:191], v[70:73]
	s_waitcnt lgkmcnt(1)
	v_mfma_f32_16x16x32_bf16 v[70:73], v[6:9], v[200:203], v[196:199]
	s_waitcnt lgkmcnt(0)
	v_mfma_f32_16x16x32_bf16 v[78:81], v[14:17], v[236:239], v[70:73]
	v_mfma_f32_16x16x32_bf16 v[70:73], v[180:183], v[200:203], v[98:101]
	v_mfma_f32_16x16x32_bf16 v[70:73], v[184:187], v[236:239], v[70:73]
	s_setprio 0
	s_barrier
	ds_read_b128 v[130:133], v151 offset:49152
	ds_read_b128 v[160:163], v151 offset:50176
	ds_read_b128 v[196:199], v151 offset:51200
	ds_read_b128 v[148:151], v151 offset:52224
	s_waitcnt vmcnt(0)
	s_barrier
	s_waitcnt lgkmcnt(0)
	s_setprio 1
	s_waitcnt lgkmcnt(3)
	v_mfma_f32_16x16x32_bf16 v[98:101], v[130:133], v[22:25], v[222:225]
	s_waitcnt lgkmcnt(1)
	v_mfma_f32_16x16x32_bf16 v[22:25], v[196:199], v[22:25], v[90:93]
	s_waitcnt lgkmcnt(0)
	v_mfma_f32_16x16x32_bf16 v[114:117], v[148:151], v[30:33], v[22:25]
	v_mfma_f32_16x16x32_bf16 v[22:25], v[130:133], v[38:41], v[164:167]
	v_mfma_f32_16x16x32_bf16 v[106:109], v[160:163], v[46:49], v[22:25]
	v_mfma_f32_16x16x32_bf16 v[22:25], v[196:199], v[38:41], v[82:85]
	v_mfma_f32_16x16x32_bf16 v[122:125], v[160:163], v[30:33], v[98:101]
	v_mfma_f32_16x16x32_bf16 v[98:101], v[148:151], v[46:49], v[22:25]
	v_mfma_f32_16x16x32_bf16 v[22:25], v[130:133], v[54:57], v[168:171]
	v_mfma_f32_16x16x32_bf16 v[90:93], v[160:163], v[188:191], v[22:25]
	v_mfma_f32_16x16x32_bf16 v[22:25], v[196:199], v[54:57], v[74:77]
	v_mfma_f32_16x16x32_bf16 v[82:85], v[148:151], v[188:191], v[22:25]
	v_mfma_f32_16x16x32_bf16 v[22:25], v[130:133], v[200:203], v[172:175]
	v_mfma_f32_16x16x32_bf16 v[74:77], v[160:163], v[236:239], v[22:25]
	v_mfma_f32_16x16x32_bf16 v[22:25], v[196:199], v[200:203], v[66:69]
	v_mfma_f32_16x16x32_bf16 v[66:69], v[148:151], v[236:239], v[22:25]
	s_setprio 0
	s_barrier
	ds_read_b128 v[164:167], v0 offset:49152
	ds_read_b128 v[168:171], v0 offset:50176
	ds_read_b128 v[172:175], v0 offset:51200
	ds_read_b128 v[188:191], v0 offset:52224
	ds_read_b128 v[200:203], v0 offset:53248
	ds_read_b128 v[222:225], v0 offset:54272
	ds_read_b128 v[236:239], v0 offset:55296
	ds_read_b128 v[240:243], v0 offset:56320
	s_barrier
	s_waitcnt lgkmcnt(0)
	s_setprio 1
	s_waitcnt lgkmcnt(7)
	v_mfma_f32_16x16x32_bf16 v[22:25], v[6:9], v[164:167], v[62:65]
	s_waitcnt lgkmcnt(6)
	v_mfma_f32_16x16x32_bf16 v[62:65], v[14:17], v[168:171], v[22:25]
	v_mfma_f32_16x16x32_bf16 v[22:25], v[180:183], v[164:167], v[58:61]
	v_mfma_f32_16x16x32_bf16 v[54:57], v[184:187], v[168:171], v[22:25]
	s_waitcnt lgkmcnt(5)
	v_mfma_f32_16x16x32_bf16 v[22:25], v[6:9], v[172:175], v[192:195]
	s_waitcnt lgkmcnt(4)
	v_mfma_f32_16x16x32_bf16 v[46:49], v[14:17], v[188:191], v[22:25]
	v_mfma_f32_16x16x32_bf16 v[22:25], v[180:183], v[172:175], v[50:53]
	v_mfma_f32_16x16x32_bf16 v[38:41], v[184:187], v[188:191], v[22:25]
	s_waitcnt lgkmcnt(3)
	v_mfma_f32_16x16x32_bf16 v[22:25], v[6:9], v[200:203], v[232:235]
	s_waitcnt lgkmcnt(1)
	v_mfma_f32_16x16x32_bf16 v[6:9], v[6:9], v[236:239], v[134:137]
	v_mfma_f32_16x16x32_bf16 v[30:33], v[14:17], v[222:225], v[22:25]
	v_mfma_f32_16x16x32_bf16 v[22:25], v[180:183], v[200:203], v[42:45]
	s_waitcnt lgkmcnt(0)
	v_mfma_f32_16x16x32_bf16 v[14:17], v[14:17], v[240:243], v[6:9]
	v_mfma_f32_16x16x32_bf16 v[6:9], v[180:183], v[236:239], v[34:37]
	v_mfma_f32_16x16x32_bf16 v[22:25], v[184:187], v[222:225], v[22:25]
	v_mfma_f32_16x16x32_bf16 v[6:9], v[184:187], v[240:243], v[6:9]
	s_setprio 0
	s_setprio 1
	v_mfma_f32_16x16x32_bf16 v[34:37], v[130:133], v[164:167], v[138:141]
	v_mfma_f32_16x16x32_bf16 v[26:29], v[196:199], v[164:167], v[26:29]
	v_mfma_f32_16x16x32_bf16 v[18:21], v[196:199], v[172:175], v[18:21]
	v_mfma_f32_16x16x32_bf16 v[58:61], v[160:163], v[168:171], v[34:37]
	v_mfma_f32_16x16x32_bf16 v[50:53], v[148:151], v[168:171], v[26:29]
	v_mfma_f32_16x16x32_bf16 v[26:29], v[130:133], v[172:175], v[152:155]
	v_mfma_f32_16x16x32_bf16 v[34:37], v[148:151], v[188:191], v[18:21]
	v_mfma_f32_16x16x32_bf16 v[18:21], v[130:133], v[200:203], v[156:159]
	v_mfma_f32_16x16x32_bf16 v[10:13], v[196:199], v[200:203], v[10:13]
	v_mfma_f32_16x16x32_bf16 v[42:45], v[160:163], v[188:191], v[26:29]
	v_mfma_f32_16x16x32_bf16 v[26:29], v[160:163], v[222:225], v[18:21]
	v_mfma_f32_16x16x32_bf16 v[18:21], v[148:151], v[222:225], v[10:13]
	v_mfma_f32_16x16x32_bf16 v[10:13], v[130:133], v[236:239], v[176:179]
	v_mfma_f32_16x16x32_bf16 v[2:5], v[196:199], v[236:239], v[2:5]
	v_mfma_f32_16x16x32_bf16 v[10:13], v[160:163], v[240:243], v[10:13]
	v_mfma_f32_16x16x32_bf16 v[2:5], v[148:151], v[240:243], v[2:5]
	s_setprio 0
	s_movk_i32 s0, 0x100
	v_cmp_gt_u32_e32 vcc, s0, v142
	s_barrier
	s_and_saveexec_b64 s[0:1], vcc
	s_cbranch_execz .LBB0_183
	s_barrier

.LBB0_678:
	ds_read_b128 v[164:167], v151
	ds_read_b128 v[168:171], v151 offset:1024
	ds_read_b128 v[172:175], v151 offset:2048
	ds_read_b128 v[176:179], v151 offset:3072
	v_lshl_add_u64 v[204:205], v[138:139], 0, s[8:9]
	v_lshl_add_u64 v[218:219], v[204:205], 0, s[60:61]
	s_add_i32 m0, s1, 0xc000
	ds_read_b128 v[180:183], v0
	ds_read_b128 v[184:187], v0 offset:1024
	ds_read_b128 v[188:191], v0 offset:2048
	ds_read_b128 v[192:195], v0 offset:3072
	ds_read_b128 v[196:199], v0 offset:4096
	ds_read_b128 v[200:203], v0 offset:5120
	ds_read_b128 v[232:235], v0 offset:6144
	ds_read_b128 v[236:239], v0 offset:7168
	global_load_lds_dwordx4 v[218:219], off
	v_lshl_add_u64 v[216:217], v[140:141], 0, s[8:9]
	s_add_i32 m0, s1, 0xe000
	v_lshl_add_u64 v[152:153], v[216:217], 0, s[60:61]
	global_load_lds_dwordx4 v[152:153], off
	s_waitcnt lgkmcnt(8)
	s_barrier
	s_waitcnt lgkmcnt(0)
	v_mfma_f32_16x16x32_bf16 v[126:129], v[164:167], v[180:183], v[126:129]
	v_mfma_f32_16x16x32_bf16 v[122:125], v[172:175], v[180:183], v[122:125]
	v_mfma_f32_16x16x32_bf16 v[118:121], v[164:167], v[188:191], v[118:121]
	ds_read_b128 v[240:243], v151 offset:16384
	v_mfma_f32_16x16x32_bf16 v[114:117], v[172:175], v[188:191], v[114:117]
	v_mfma_f32_16x16x32_bf16 v[110:113], v[164:167], v[196:199], v[110:113]
	v_mfma_f32_16x16x32_bf16 v[106:109], v[172:175], v[196:199], v[106:109]
	ds_read_b128 v[244:247], v151 offset:17408
	v_mfma_f32_16x16x32_bf16 v[102:105], v[164:167], v[232:235], v[102:105]
	v_mfma_f32_16x16x32_bf16 v[98:101], v[172:175], v[232:235], v[98:101]
	v_mfma_f32_16x16x32_bf16 v[126:129], v[168:171], v[184:187], v[126:129]
	ds_read_b128 v[248:251], v151 offset:18432
	v_mfma_f32_16x16x32_bf16 v[122:125], v[176:179], v[184:187], v[122:125]
	v_mfma_f32_16x16x32_bf16 v[118:121], v[168:171], v[192:195], v[118:121]
	v_mfma_f32_16x16x32_bf16 v[114:117], v[176:179], v[192:195], v[114:117]
	ds_read_b128 v[222:225], v151 offset:19456
	v_mfma_f32_16x16x32_bf16 v[110:113], v[168:171], v[200:203], v[110:113]
	v_mfma_f32_16x16x32_bf16 v[106:109], v[176:179], v[200:203], v[106:109]
	v_mfma_f32_16x16x32_bf16 v[102:105], v[168:171], v[236:239], v[102:105]
	v_mfma_f32_16x16x32_bf16 v[98:101], v[176:179], v[236:239], v[98:101]
	s_barrier
	v_lshl_add_u64 v[210:211], v[134:135], 0, s[8:9]
	s_add_i32 m0, s1, 0xff00
	global_load_lds_dwordx4 v[210:211], off offset:256
	s_add_i32 m0, s1, 0x11f00
	v_lshl_add_u64 v[228:229], v[136:137], 0, s[8:9]
	global_load_lds_dwordx4 v[228:229], off offset:256
	s_barrier
	s_waitcnt lgkmcnt(0)
	v_mfma_f32_16x16x32_bf16 v[94:97], v[240:243], v[180:183], v[94:97]
	v_mfma_f32_16x16x32_bf16 v[90:93], v[248:251], v[180:183], v[90:93]
	v_mfma_f32_16x16x32_bf16 v[86:89], v[240:243], v[188:191], v[86:89]
	v_mfma_f32_16x16x32_bf16 v[82:85], v[248:251], v[188:191], v[82:85]
	v_mfma_f32_16x16x32_bf16 v[78:81], v[240:243], v[196:199], v[78:81]
	v_mfma_f32_16x16x32_bf16 v[74:77], v[248:251], v[196:199], v[74:77]
	v_mfma_f32_16x16x32_bf16 v[70:73], v[240:243], v[232:235], v[70:73]
	v_mfma_f32_16x16x32_bf16 v[66:69], v[248:251], v[232:235], v[66:69]
	v_mfma_f32_16x16x32_bf16 v[94:97], v[244:247], v[184:187], v[94:97]
	v_mfma_f32_16x16x32_bf16 v[90:93], v[222:225], v[184:187], v[90:93]
	v_mfma_f32_16x16x32_bf16 v[86:89], v[244:247], v[192:195], v[86:89]
	v_mfma_f32_16x16x32_bf16 v[82:85], v[222:225], v[192:195], v[82:85]
	v_mfma_f32_16x16x32_bf16 v[78:81], v[244:247], v[200:203], v[78:81]
	v_mfma_f32_16x16x32_bf16 v[74:77], v[222:225], v[200:203], v[74:77]
	v_mfma_f32_16x16x32_bf16 v[70:73], v[244:247], v[236:239], v[70:73]
	v_mfma_f32_16x16x32_bf16 v[66:69], v[222:225], v[236:239], v[66:69]
	v_lshl_add_u64 v[158:159], v[204:205], 0, s[74:75]
	s_mov_b32 m0, s1
	s_barrier
	ds_read_b128 v[180:183], v0 offset:16384
	ds_read_b128 v[184:187], v0 offset:17408
	ds_read_b128 v[188:191], v0 offset:18432
	ds_read_b128 v[192:195], v0 offset:19456
	ds_read_b128 v[196:199], v0 offset:20480
	ds_read_b128 v[200:203], v0 offset:21504
	ds_read_b128 v[232:235], v0 offset:22528
	ds_read_b128 v[236:239], v0 offset:23552
	global_load_lds_dwordx4 v[158:159], off
	s_add_i32 m0, s1, 0x1f00
	s_nop 0
	global_load_lds_dwordx4 v[216:217], off offset:256
	s_barrier
	s_waitcnt lgkmcnt(0)
	v_mfma_f32_16x16x32_bf16 v[62:65], v[164:167], v[180:183], v[62:65]
	v_mfma_f32_16x16x32_bf16 v[58:61], v[172:175], v[180:183], v[58:61]
	v_mfma_f32_16x16x32_bf16 v[54:57], v[164:167], v[188:191], v[54:57]
	v_mfma_f32_16x16x32_bf16 v[50:53], v[172:175], v[188:191], v[50:53]
	v_mfma_f32_16x16x32_bf16 v[46:49], v[164:167], v[196:199], v[46:49]
	v_mfma_f32_16x16x32_bf16 v[42:45], v[172:175], v[196:199], v[42:45]
	v_mfma_f32_16x16x32_bf16 v[38:41], v[164:167], v[232:235], v[38:41]
	v_mfma_f32_16x16x32_bf16 v[34:37], v[172:175], v[232:235], v[34:37]
	v_mfma_f32_16x16x32_bf16 v[62:65], v[168:171], v[184:187], v[62:65]
	v_mfma_f32_16x16x32_bf16 v[58:61], v[176:179], v[184:187], v[58:61]
	v_mfma_f32_16x16x32_bf16 v[54:57], v[168:171], v[192:195], v[54:57]
	v_mfma_f32_16x16x32_bf16 v[50:53], v[176:179], v[192:195], v[50:53]
	v_mfma_f32_16x16x32_bf16 v[46:49], v[168:171], v[200:203], v[46:49]
	v_mfma_f32_16x16x32_bf16 v[42:45], v[176:179], v[200:203], v[42:45]
	v_mfma_f32_16x16x32_bf16 v[38:41], v[168:171], v[236:239], v[38:41]
	v_mfma_f32_16x16x32_bf16 v[34:37], v[176:179], v[236:239], v[34:37]
	s_barrier
	s_add_i32 m0, s1, 0x14000
	v_lshl_add_u64 v[154:155], v[210:211], 0, s[18:19]
	global_load_lds_dwordx4 v[154:155], off
	s_add_i32 m0, s1, 0x16000
	v_lshl_add_u64 v[156:157], v[228:229], 0, s[18:19]
	global_load_lds_dwordx4 v[156:157], off
	s_waitcnt vmcnt(6)
	s_barrier
	v_mfma_f32_16x16x32_bf16 v[30:33], v[240:243], v[180:183], v[30:33]
	v_mfma_f32_16x16x32_bf16 v[26:29], v[248:251], v[180:183], v[26:29]
	v_mfma_f32_16x16x32_bf16 v[22:25], v[240:243], v[188:191], v[22:25]
	ds_read_b128 v[164:167], v151 offset:32768
	v_mfma_f32_16x16x32_bf16 v[18:21], v[248:251], v[188:191], v[18:21]
	v_mfma_f32_16x16x32_bf16 v[14:17], v[240:243], v[196:199], v[14:17]
	v_mfma_f32_16x16x32_bf16 v[10:13], v[248:251], v[196:199], v[10:13]
	ds_read_b128 v[168:171], v151 offset:33792
	v_mfma_f32_16x16x32_bf16 v[6:9], v[240:243], v[232:235], v[6:9]
	v_mfma_f32_16x16x32_bf16 v[2:5], v[248:251], v[232:235], v[2:5]
	v_mfma_f32_16x16x32_bf16 v[30:33], v[244:247], v[184:187], v[30:33]
	ds_read_b128 v[172:175], v151 offset:34816
	v_mfma_f32_16x16x32_bf16 v[26:29], v[222:225], v[184:187], v[26:29]
	v_mfma_f32_16x16x32_bf16 v[22:25], v[244:247], v[192:195], v[22:25]
	v_mfma_f32_16x16x32_bf16 v[18:21], v[222:225], v[192:195], v[18:21]
	ds_read_b128 v[176:179], v151 offset:35840
	v_mfma_f32_16x16x32_bf16 v[14:17], v[244:247], v[200:203], v[14:17]
	v_mfma_f32_16x16x32_bf16 v[10:13], v[222:225], v[200:203], v[10:13]
	v_mfma_f32_16x16x32_bf16 v[6:9], v[244:247], v[236:239], v[6:9]
	v_mfma_f32_16x16x32_bf16 v[2:5], v[222:225], v[236:239], v[2:5]
	s_barrier
	s_add_i32 m0, s1, 0x3f80
	ds_read_b128 v[180:183], v0 offset:32768
	ds_read_b128 v[184:187], v0 offset:33792
	ds_read_b128 v[188:191], v0 offset:34816
	ds_read_b128 v[192:195], v0 offset:35840
	ds_read_b128 v[196:199], v0 offset:36864
	ds_read_b128 v[200:203], v0 offset:37888
	ds_read_b128 v[222:225], v0 offset:38912
	ds_read_b128 v[232:235], v0 offset:39936
	global_load_lds_dwordx4 v[218:219], off offset:128
	s_add_i32 m0, s1, 0x5f80
	s_nop 0
	global_load_lds_dwordx4 v[152:153], off offset:128
	s_waitcnt lgkmcnt(8)
	s_barrier
	s_waitcnt lgkmcnt(0)
	v_mfma_f32_16x16x32_bf16 v[126:129], v[164:167], v[180:183], v[126:129]
	v_mfma_f32_16x16x32_bf16 v[122:125], v[172:175], v[180:183], v[122:125]
	v_mfma_f32_16x16x32_bf16 v[118:121], v[164:167], v[188:191], v[118:121]
	ds_read_b128 v[236:239], v151 offset:49152
	v_mfma_f32_16x16x32_bf16 v[114:117], v[172:175], v[188:191], v[114:117]
	v_mfma_f32_16x16x32_bf16 v[110:113], v[164:167], v[196:199], v[110:113]
	v_mfma_f32_16x16x32_bf16 v[106:109], v[172:175], v[196:199], v[106:109]
	ds_read_b128 v[240:243], v151 offset:50176
	v_mfma_f32_16x16x32_bf16 v[102:105], v[164:167], v[222:225], v[102:105]
	v_mfma_f32_16x16x32_bf16 v[98:101], v[172:175], v[222:225], v[98:101]
	v_mfma_f32_16x16x32_bf16 v[126:129], v[168:171], v[184:187], v[126:129]
	ds_read_b128 v[244:247], v151 offset:51200
	v_mfma_f32_16x16x32_bf16 v[122:125], v[176:179], v[184:187], v[122:125]
	v_mfma_f32_16x16x32_bf16 v[118:121], v[168:171], v[192:195], v[118:121]
	v_mfma_f32_16x16x32_bf16 v[114:117], v[176:179], v[192:195], v[114:117]
	ds_read_b128 v[248:251], v151 offset:52224
	v_mfma_f32_16x16x32_bf16 v[110:113], v[168:171], v[200:203], v[110:113]
	v_mfma_f32_16x16x32_bf16 v[106:109], v[176:179], v[200:203], v[106:109]
	v_mfma_f32_16x16x32_bf16 v[102:105], v[168:171], v[232:235], v[102:105]
	v_mfma_f32_16x16x32_bf16 v[98:101], v[176:179], v[232:235], v[98:101]
	s_barrier
	s_add_i32 m0, s1, 0x17e80
	global_load_lds_dwordx4 v[210:211], off offset:384
	s_add_i32 m0, s1, 0x19e80
	s_nop 0
	global_load_lds_dwordx4 v[228:229], off offset:384
	s_barrier
	s_waitcnt lgkmcnt(0)
	v_mfma_f32_16x16x32_bf16 v[94:97], v[236:239], v[180:183], v[94:97]
	v_mfma_f32_16x16x32_bf16 v[90:93], v[244:247], v[180:183], v[90:93]
	v_mfma_f32_16x16x32_bf16 v[86:89], v[236:239], v[188:191], v[86:89]
	v_mfma_f32_16x16x32_bf16 v[82:85], v[244:247], v[188:191], v[82:85]
	v_mfma_f32_16x16x32_bf16 v[78:81], v[236:239], v[196:199], v[78:81]
	v_mfma_f32_16x16x32_bf16 v[74:77], v[244:247], v[196:199], v[74:77]
	v_mfma_f32_16x16x32_bf16 v[70:73], v[236:239], v[222:225], v[70:73]
	v_mfma_f32_16x16x32_bf16 v[66:69], v[244:247], v[222:225], v[66:69]
	v_mfma_f32_16x16x32_bf16 v[94:97], v[240:243], v[184:187], v[94:97]
	v_mfma_f32_16x16x32_bf16 v[90:93], v[248:251], v[184:187], v[90:93]
	v_mfma_f32_16x16x32_bf16 v[86:89], v[240:243], v[192:195], v[86:89]
	v_mfma_f32_16x16x32_bf16 v[82:85], v[248:251], v[192:195], v[82:85]
	v_mfma_f32_16x16x32_bf16 v[78:81], v[240:243], v[200:203], v[78:81]
	v_mfma_f32_16x16x32_bf16 v[74:77], v[248:251], v[200:203], v[74:77]
	v_mfma_f32_16x16x32_bf16 v[70:73], v[240:243], v[232:235], v[70:73]
	v_mfma_f32_16x16x32_bf16 v[66:69], v[248:251], v[232:235], v[66:69]
	s_add_i32 m0, s1, 0x7e80
	s_barrier
	ds_read_b128 v[180:183], v0 offset:49152
	ds_read_b128 v[184:187], v0 offset:50176
	ds_read_b128 v[188:191], v0 offset:51200
	ds_read_b128 v[192:195], v0 offset:52224
	ds_read_b128 v[196:199], v0 offset:53248
	ds_read_b128 v[200:203], v0 offset:54272
	ds_read_b128 v[222:225], v0 offset:55296
	ds_read_b128 v[232:235], v0 offset:56320
	global_load_lds_dwordx4 v[204:205], off offset:384
	s_add_i32 m0, s1, 0x9e80
	s_nop 0
	global_load_lds_dwordx4 v[216:217], off offset:384
	s_barrier
	s_waitcnt lgkmcnt(0)
	v_mfma_f32_16x16x32_bf16 v[62:65], v[164:167], v[180:183], v[62:65]
	v_mfma_f32_16x16x32_bf16 v[58:61], v[172:175], v[180:183], v[58:61]
	v_mfma_f32_16x16x32_bf16 v[54:57], v[164:167], v[188:191], v[54:57]
	v_mfma_f32_16x16x32_bf16 v[50:53], v[172:175], v[188:191], v[50:53]
	v_mfma_f32_16x16x32_bf16 v[46:49], v[164:167], v[196:199], v[46:49]
	v_mfma_f32_16x16x32_bf16 v[42:45], v[172:175], v[196:199], v[42:45]
	v_mfma_f32_16x16x32_bf16 v[38:41], v[164:167], v[222:225], v[38:41]
	v_mfma_f32_16x16x32_bf16 v[34:37], v[172:175], v[222:225], v[34:37]
	v_mfma_f32_16x16x32_bf16 v[62:65], v[168:171], v[184:187], v[62:65]
	v_mfma_f32_16x16x32_bf16 v[58:61], v[176:179], v[184:187], v[58:61]
	v_mfma_f32_16x16x32_bf16 v[54:57], v[168:171], v[192:195], v[54:57]
	v_mfma_f32_16x16x32_bf16 v[50:53], v[176:179], v[192:195], v[50:53]
	v_mfma_f32_16x16x32_bf16 v[46:49], v[168:171], v[200:203], v[46:49]
	v_mfma_f32_16x16x32_bf16 v[42:45], v[176:179], v[200:203], v[42:45]
	v_mfma_f32_16x16x32_bf16 v[38:41], v[168:171], v[232:235], v[38:41]
	v_mfma_f32_16x16x32_bf16 v[34:37], v[176:179], v[232:235], v[34:37]
	s_barrier
	s_add_i32 m0, s1, 0x1bf80
	s_nop 0
	global_load_lds_dwordx4 v[154:155], off offset:128
	s_add_i32 m0, s1, 0x1df80
	s_nop 0
	global_load_lds_dwordx4 v[156:157], off offset:128
	s_waitcnt vmcnt(6)
	s_barrier
	v_mfma_f32_16x16x32_bf16 v[30:33], v[236:239], v[180:183], v[30:33]
	v_mfma_f32_16x16x32_bf16 v[26:29], v[244:247], v[180:183], v[26:29]
	v_mfma_f32_16x16x32_bf16 v[22:25], v[236:239], v[188:191], v[22:25]
	v_mfma_f32_16x16x32_bf16 v[18:21], v[244:247], v[188:191], v[18:21]
	v_mfma_f32_16x16x32_bf16 v[14:17], v[236:239], v[196:199], v[14:17]
	v_mfma_f32_16x16x32_bf16 v[10:13], v[244:247], v[196:199], v[10:13]
	v_mfma_f32_16x16x32_bf16 v[6:9], v[236:239], v[222:225], v[6:9]
	v_mfma_f32_16x16x32_bf16 v[2:5], v[244:247], v[222:225], v[2:5]
	v_mfma_f32_16x16x32_bf16 v[30:33], v[240:243], v[184:187], v[30:33]
	v_mfma_f32_16x16x32_bf16 v[26:29], v[248:251], v[184:187], v[26:29]
	v_mfma_f32_16x16x32_bf16 v[22:25], v[240:243], v[192:195], v[22:25]
	v_mfma_f32_16x16x32_bf16 v[18:21], v[248:251], v[192:195], v[18:21]
	v_mfma_f32_16x16x32_bf16 v[14:17], v[240:243], v[200:203], v[14:17]
	v_mfma_f32_16x16x32_bf16 v[10:13], v[248:251], v[200:203], v[10:13]
	v_mfma_f32_16x16x32_bf16 v[6:9], v[240:243], v[232:235], v[6:9]
	v_mfma_f32_16x16x32_bf16 v[2:5], v[248:251], v[232:235], v[2:5]
	s_add_i32 s0, s0, 2
	s_add_u32 s8, s8, 0x100
	s_addc_u32 s9, s9, 0
	s_cmp_lt_u32 s0, 28
	s_barrier
	s_cbranch_scc1 .LBB0_678
	s_add_i32 s1, s1, 0x1e000
	s_mov_b64 s[8:9], 0xf80
	v_readfirstlane_b32 s0, v162
	v_lshl_add_u64 v[132:133], v[132:133], 0, s[8:9]
	s_mov_b32 m0, s0
	v_readfirstlane_b32 s0, v163
	ds_read_b128 v[134:137], v151
	ds_read_b128 v[138:141], v151 offset:1024
	ds_read_b128 v[152:155], v151 offset:2048
	ds_read_b128 v[156:159], v151 offset:3072
	ds_read_b128 v[164:167], v0
	ds_read_b128 v[168:171], v0 offset:1024
	ds_read_b128 v[172:175], v0 offset:2048
	ds_read_b128 v[176:179], v0 offset:3072
	ds_read_b128 v[180:183], v0 offset:4096
	ds_read_b128 v[184:187], v0 offset:5120
	ds_read_b128 v[188:191], v0 offset:6144
	ds_read_b128 v[192:195], v0 offset:7168
	global_load_lds_dwordx4 v[132:133], off
	v_lshl_add_u64 v[130:131], v[130:131], 0, s[8:9]
	s_mov_b32 m0, s0
	s_nop 0
	global_load_lds_dwordx4 v[130:131], off
	s_barrier
	s_waitcnt lgkmcnt(0)
	s_setprio 1
	s_waitcnt lgkmcnt(0)
	v_mfma_f32_16x16x32_bf16 v[126:129], v[134:137], v[164:167], v[126:129]
	v_mfma_f32_16x16x32_bf16 v[122:125], v[152:155], v[164:167], v[122:125]
	v_mfma_f32_16x16x32_bf16 v[114:117], v[152:155], v[172:175], v[114:117]
	v_mfma_f32_16x16x32_bf16 v[106:109], v[152:155], v[180:183], v[106:109]
	v_mfma_f32_16x16x32_bf16 v[98:101], v[152:155], v[188:191], v[98:101]
	v_mfma_f32_16x16x32_bf16 v[126:129], v[138:141], v[168:171], v[126:129]
	v_mfma_f32_16x16x32_bf16 v[122:125], v[156:159], v[168:171], v[122:125]
	v_mfma_f32_16x16x32_bf16 v[118:121], v[134:137], v[172:175], v[118:121]
	v_mfma_f32_16x16x32_bf16 v[114:117], v[156:159], v[176:179], v[114:117]
	v_mfma_f32_16x16x32_bf16 v[110:113], v[134:137], v[180:183], v[110:113]
	v_mfma_f32_16x16x32_bf16 v[106:109], v[156:159], v[184:187], v[106:109]
	v_mfma_f32_16x16x32_bf16 v[102:105], v[134:137], v[188:191], v[102:105]
	v_mfma_f32_16x16x32_bf16 v[98:101], v[156:159], v[192:195], v[98:101]
	v_mfma_f32_16x16x32_bf16 v[130:133], v[138:141], v[176:179], v[118:121]
	v_mfma_f32_16x16x32_bf16 v[160:163], v[138:141], v[184:187], v[110:113]
	v_mfma_f32_16x16x32_bf16 v[196:199], v[138:141], v[192:195], v[102:105]
	s_setprio 0
	s_barrier
	s_nop 0
	ds_read_b128 v[102:105], v151 offset:16384
	ds_read_b128 v[110:113], v151 offset:17408
	ds_read_b128 v[118:121], v151 offset:18432
	ds_read_b128 v[200:203], v151 offset:19456
	s_barrier
	s_waitcnt lgkmcnt(0)
	s_setprio 1
	s_waitcnt lgkmcnt(1)
	v_mfma_f32_16x16x32_bf16 v[90:93], v[118:121], v[164:167], v[90:93]
	v_mfma_f32_16x16x32_bf16 v[86:89], v[102:105], v[172:175], v[86:89]
	v_mfma_f32_16x16x32_bf16 v[82:85], v[118:121], v[172:175], v[82:85]
	v_mfma_f32_16x16x32_bf16 v[78:81], v[102:105], v[180:183], v[78:81]
	v_mfma_f32_16x16x32_bf16 v[70:73], v[102:105], v[188:191], v[70:73]
	v_mfma_f32_16x16x32_bf16 v[94:97], v[102:105], v[164:167], v[94:97]
	s_waitcnt lgkmcnt(0)
	v_mfma_f32_16x16x32_bf16 v[90:93], v[200:203], v[168:171], v[90:93]
	v_mfma_f32_16x16x32_bf16 v[86:89], v[110:113], v[176:179], v[86:89]
	v_mfma_f32_16x16x32_bf16 v[82:85], v[200:203], v[176:179], v[82:85]
	v_mfma_f32_16x16x32_bf16 v[78:81], v[110:113], v[184:187], v[78:81]
	v_mfma_f32_16x16x32_bf16 v[74:77], v[118:121], v[180:183], v[74:77]
	v_mfma_f32_16x16x32_bf16 v[70:73], v[110:113], v[192:195], v[70:73]
	v_mfma_f32_16x16x32_bf16 v[66:69], v[118:121], v[188:191], v[66:69]
	v_mfma_f32_16x16x32_bf16 v[222:225], v[110:113], v[168:171], v[94:97]
	v_mfma_f32_16x16x32_bf16 v[164:167], v[200:203], v[184:187], v[74:77]
	v_mfma_f32_16x16x32_bf16 v[168:171], v[200:203], v[192:195], v[66:69]
	s_setprio 0
	s_barrier
	s_nop 2
	ds_read_b128 v[66:69], v0 offset:16384
	ds_read_b128 v[74:77], v0 offset:17408
	ds_read_b128 v[94:97], v0 offset:18432
	ds_read_b128 v[172:175], v0 offset:19456
	ds_read_b128 v[176:179], v0 offset:20480
	ds_read_b128 v[180:183], v0 offset:21504
	ds_read_b128 v[184:187], v0 offset:22528
	ds_read_b128 v[188:191], v0 offset:23552
	s_waitcnt vmcnt(4)
	s_barrier
	s_waitcnt lgkmcnt(0)
	s_setprio 1
	s_waitcnt lgkmcnt(5)
	v_mfma_f32_16x16x32_bf16 v[54:57], v[134:137], v[94:97], v[54:57]
	v_mfma_f32_16x16x32_bf16 v[50:53], v[152:155], v[94:97], v[50:53]
	v_mfma_f32_16x16x32_bf16 v[62:65], v[134:137], v[66:69], v[62:65]
	v_mfma_f32_16x16x32_bf16 v[58:61], v[152:155], v[66:69], v[58:61]
	s_waitcnt lgkmcnt(4)
	v_mfma_f32_16x16x32_bf16 v[54:57], v[138:141], v[172:175], v[54:57]
	v_mfma_f32_16x16x32_bf16 v[50:53], v[156:159], v[172:175], v[50:53]
	s_waitcnt lgkmcnt(3)
	v_mfma_f32_16x16x32_bf16 v[46:49], v[134:137], v[176:179], v[46:49]
	v_mfma_f32_16x16x32_bf16 v[42:45], v[152:155], v[176:179], v[42:45]
	s_waitcnt lgkmcnt(1)
	v_mfma_f32_16x16x32_bf16 v[38:41], v[134:137], v[184:187], v[38:41]
	v_mfma_f32_16x16x32_bf16 v[34:37], v[152:155], v[184:187], v[34:37]
	v_mfma_f32_16x16x32_bf16 v[192:195], v[138:141], v[74:77], v[62:65]
	v_mfma_f32_16x16x32_bf16 v[232:235], v[156:159], v[74:77], v[58:61]
	v_mfma_f32_16x16x32_bf16 v[236:239], v[138:141], v[180:183], v[46:49]
	v_mfma_f32_16x16x32_bf16 v[240:243], v[156:159], v[180:183], v[42:45]
	s_waitcnt lgkmcnt(0)
	v_mfma_f32_16x16x32_bf16 v[134:137], v[138:141], v[188:191], v[38:41]
	v_mfma_f32_16x16x32_bf16 v[138:141], v[156:159], v[188:191], v[34:37]
	s_setprio 0
	s_setprio 1
	v_mfma_f32_16x16x32_bf16 v[30:33], v[102:105], v[66:69], v[30:33]
	v_mfma_f32_16x16x32_bf16 v[26:29], v[118:121], v[66:69], v[26:29]
	v_mfma_f32_16x16x32_bf16 v[14:17], v[102:105], v[176:179], v[14:17]
	v_mfma_f32_16x16x32_bf16 v[10:13], v[118:121], v[176:179], v[10:13]
	v_mfma_f32_16x16x32_bf16 v[30:33], v[110:113], v[74:77], v[30:33]
	v_mfma_f32_16x16x32_bf16 v[26:29], v[200:203], v[74:77], v[26:29]
	v_mfma_f32_16x16x32_bf16 v[22:25], v[102:105], v[94:97], v[22:25]
	v_mfma_f32_16x16x32_bf16 v[18:21], v[118:121], v[94:97], v[18:21]
	v_mfma_f32_16x16x32_bf16 v[14:17], v[110:113], v[180:183], v[14:17]
	v_mfma_f32_16x16x32_bf16 v[10:13], v[200:203], v[180:183], v[10:13]
	v_mfma_f32_16x16x32_bf16 v[6:9], v[102:105], v[184:187], v[6:9]
	v_mfma_f32_16x16x32_bf16 v[2:5], v[118:121], v[184:187], v[2:5]
	v_mfma_f32_16x16x32_bf16 v[152:155], v[110:113], v[172:175], v[22:25]
	v_mfma_f32_16x16x32_bf16 v[156:159], v[200:203], v[172:175], v[18:21]
	v_mfma_f32_16x16x32_bf16 v[172:175], v[110:113], v[188:191], v[6:9]
	v_mfma_f32_16x16x32_bf16 v[176:179], v[200:203], v[188:191], v[2:5]
	s_setprio 0
	s_barrier
	s_nop 1
	ds_read_b128 v[2:5], v151 offset:32768
	ds_read_b128 v[6:9], v151 offset:33792
	ds_read_b128 v[180:183], v151 offset:34816
	ds_read_b128 v[184:187], v151 offset:35840
	ds_read_b128 v[18:21], v0 offset:32768
	ds_read_b128 v[22:25], v0 offset:33792
	ds_read_b128 v[38:41], v0 offset:34816
	ds_read_b128 v[46:49], v0 offset:35840
	ds_read_b128 v[58:61], v0 offset:36864
	ds_read_b128 v[66:69], v0 offset:37888
	ds_read_b128 v[188:191], v0 offset:38912
	ds_read_b128 v[200:203], v0 offset:39936
	s_waitcnt vmcnt(2)
	s_barrier
	s_waitcnt lgkmcnt(0)
	s_setprio 1
	s_waitcnt lgkmcnt(7)
	v_mfma_f32_16x16x32_bf16 v[34:37], v[2:5], v[18:21], v[126:129]
	s_waitcnt lgkmcnt(6)
	v_mfma_f32_16x16x32_bf16 v[118:121], v[6:9], v[22:25], v[34:37]
	v_mfma_f32_16x16x32_bf16 v[34:37], v[180:183], v[18:21], v[122:125]
	v_mfma_f32_16x16x32_bf16 v[110:113], v[184:187], v[22:25], v[34:37]
	s_waitcnt lgkmcnt(5)
	v_mfma_f32_16x16x32_bf16 v[34:37], v[2:5], v[38:41], v[130:133]
	s_waitcnt lgkmcnt(4)
	v_mfma_f32_16x16x32_bf16 v[102:105], v[6:9], v[46:49], v[34:37]
	v_mfma_f32_16x16x32_bf16 v[34:37], v[180:183], v[38:41], v[114:117]
	v_mfma_f32_16x16x32_bf16 v[94:97], v[184:187], v[46:49], v[34:37]
	s_waitcnt lgkmcnt(3)
	v_mfma_f32_16x16x32_bf16 v[34:37], v[2:5], v[58:61], v[160:163]
	s_waitcnt lgkmcnt(2)
	v_mfma_f32_16x16x32_bf16 v[74:77], v[6:9], v[66:69], v[34:37]
	v_mfma_f32_16x16x32_bf16 v[34:37], v[180:183], v[58:61], v[106:109]
	v_mfma_f32_16x16x32_bf16 v[62:65], v[184:187], v[66:69], v[34:37]
	s_waitcnt lgkmcnt(1)
	v_mfma_f32_16x16x32_bf16 v[34:37], v[2:5], v[188:191], v[196:199]
	s_waitcnt lgkmcnt(0)
	v_mfma_f32_16x16x32_bf16 v[42:45], v[6:9], v[200:203], v[34:37]
	v_mfma_f32_16x16x32_bf16 v[34:37], v[180:183], v[188:191], v[98:101]
	v_mfma_f32_16x16x32_bf16 v[34:37], v[184:187], v[200:203], v[34:37]
	s_setprio 0
	s_barrier
	ds_read_b128 v[130:133], v151 offset:49152
	ds_read_b128 v[160:163], v151 offset:50176
	ds_read_b128 v[196:199], v151 offset:51200
	ds_read_b128 v[148:151], v151 offset:52224
	s_waitcnt vmcnt(0)
	s_barrier
	s_waitcnt lgkmcnt(0)
	s_setprio 1
	s_waitcnt lgkmcnt(3)
	v_mfma_f32_16x16x32_bf16 v[98:101], v[130:133], v[18:21], v[222:225]
	s_waitcnt lgkmcnt(1)
	v_mfma_f32_16x16x32_bf16 v[18:21], v[196:199], v[18:21], v[90:93]
	s_waitcnt lgkmcnt(0)
	v_mfma_f32_16x16x32_bf16 v[122:125], v[148:151], v[22:25], v[18:21]
	v_mfma_f32_16x16x32_bf16 v[18:21], v[130:133], v[38:41], v[86:89]
	v_mfma_f32_16x16x32_bf16 v[114:117], v[160:163], v[46:49], v[18:21]
	v_mfma_f32_16x16x32_bf16 v[18:21], v[196:199], v[38:41], v[82:85]
	v_mfma_f32_16x16x32_bf16 v[106:109], v[148:151], v[46:49], v[18:21]
	v_mfma_f32_16x16x32_bf16 v[18:21], v[130:133], v[58:61], v[78:81]
	v_mfma_f32_16x16x32_bf16 v[126:129], v[160:163], v[22:25], v[98:101]
	v_mfma_f32_16x16x32_bf16 v[98:101], v[160:163], v[66:69], v[18:21]
	v_mfma_f32_16x16x32_bf16 v[18:21], v[196:199], v[58:61], v[164:167]
	v_mfma_f32_16x16x32_bf16 v[90:93], v[148:151], v[66:69], v[18:21]
	v_mfma_f32_16x16x32_bf16 v[18:21], v[130:133], v[188:191], v[70:73]
	v_mfma_f32_16x16x32_bf16 v[66:69], v[160:163], v[200:203], v[18:21]
	v_mfma_f32_16x16x32_bf16 v[18:21], v[196:199], v[188:191], v[168:171]
	v_mfma_f32_16x16x32_bf16 v[58:61], v[148:151], v[200:203], v[18:21]
	s_setprio 0
	s_barrier
	ds_read_b128 v[82:85], v0 offset:49152
	ds_read_b128 v[164:167], v0 offset:50176
	ds_read_b128 v[168:171], v0 offset:51200
	ds_read_b128 v[188:191], v0 offset:52224
	ds_read_b128 v[200:203], v0 offset:53248
	ds_read_b128 v[222:225], v0 offset:54272
	ds_read_b128 v[244:247], v0 offset:55296
	ds_read_b128 v[248:251], v0 offset:56320
	s_barrier
	s_waitcnt lgkmcnt(0)
	s_setprio 1
	s_waitcnt lgkmcnt(7)
	v_mfma_f32_16x16x32_bf16 v[18:21], v[2:5], v[82:85], v[192:195]
	s_waitcnt lgkmcnt(6)
	v_mfma_f32_16x16x32_bf16 v[78:81], v[6:9], v[164:167], v[18:21]
	v_mfma_f32_16x16x32_bf16 v[18:21], v[180:183], v[82:85], v[232:235]
	v_mfma_f32_16x16x32_bf16 v[70:73], v[184:187], v[164:167], v[18:21]
	s_waitcnt lgkmcnt(5)
	v_mfma_f32_16x16x32_bf16 v[18:21], v[2:5], v[168:171], v[54:57]
	s_waitcnt lgkmcnt(4)
	v_mfma_f32_16x16x32_bf16 v[46:49], v[6:9], v[188:191], v[18:21]
	v_mfma_f32_16x16x32_bf16 v[18:21], v[180:183], v[168:171], v[50:53]
	v_mfma_f32_16x16x32_bf16 v[38:41], v[184:187], v[188:191], v[18:21]
	s_waitcnt lgkmcnt(3)
	v_mfma_f32_16x16x32_bf16 v[18:21], v[2:5], v[200:203], v[236:239]
	s_waitcnt lgkmcnt(1)
	v_mfma_f32_16x16x32_bf16 v[2:5], v[2:5], v[244:247], v[134:137]
	v_mfma_f32_16x16x32_bf16 v[22:25], v[6:9], v[222:225], v[18:21]
	v_mfma_f32_16x16x32_bf16 v[18:21], v[180:183], v[200:203], v[240:243]
	s_waitcnt lgkmcnt(0)
	v_mfma_f32_16x16x32_bf16 v[6:9], v[6:9], v[248:251], v[2:5]
	v_mfma_f32_16x16x32_bf16 v[2:5], v[180:183], v[244:247], v[138:141]
	v_mfma_f32_16x16x32_bf16 v[18:21], v[184:187], v[222:225], v[18:21]
	v_mfma_f32_16x16x32_bf16 v[2:5], v[184:187], v[248:251], v[2:5]
	s_setprio 0
	s_setprio 1
	v_mfma_f32_16x16x32_bf16 v[26:29], v[196:199], v[82:85], v[26:29]
	v_mfma_f32_16x16x32_bf16 v[30:33], v[130:133], v[82:85], v[30:33]
	v_mfma_f32_16x16x32_bf16 v[82:85], v[148:151], v[164:167], v[26:29]
	v_mfma_f32_16x16x32_bf16 v[26:29], v[130:133], v[168:171], v[152:155]
	v_mfma_f32_16x16x32_bf16 v[54:57], v[160:163], v[188:191], v[26:29]
	v_mfma_f32_16x16x32_bf16 v[26:29], v[196:199], v[168:171], v[156:159]
	v_mfma_f32_16x16x32_bf16 v[10:13], v[196:199], v[200:203], v[10:13]
	v_mfma_f32_16x16x32_bf16 v[50:53], v[148:151], v[188:191], v[26:29]
	v_mfma_f32_16x16x32_bf16 v[14:17], v[130:133], v[200:203], v[14:17]
	v_mfma_f32_16x16x32_bf16 v[26:29], v[148:151], v[222:225], v[10:13]
	v_mfma_f32_16x16x32_bf16 v[10:13], v[130:133], v[244:247], v[172:175]
	v_mfma_f32_16x16x32_bf16 v[86:89], v[160:163], v[164:167], v[30:33]
	v_mfma_f32_16x16x32_bf16 v[30:33], v[160:163], v[222:225], v[14:17]
	v_mfma_f32_16x16x32_bf16 v[14:17], v[160:163], v[248:251], v[10:13]
	v_mfma_f32_16x16x32_bf16 v[10:13], v[196:199], v[244:247], v[176:179]
	v_mfma_f32_16x16x32_bf16 v[10:13], v[148:151], v[248:251], v[10:13]
	s_setprio 0
	s_movk_i32 s0, 0x100
	v_cmp_gt_u32_e32 vcc, s0, v142
	s_barrier
	s_and_saveexec_b64 s[0:1], vcc
	s_cbranch_execz .LBB0_674
	s_barrier
	s_branch .LBB0_674

.LBB0_761:
	ds_read_b128 v[164:167], v148
	ds_read_b128 v[168:171], v148 offset:1024
	ds_read_b128 v[172:175], v148 offset:2048
	ds_read_b128 v[176:179], v148 offset:3072
	v_lshl_add_u64 v[204:205], v[136:137], 0, s[10:11]
	v_lshl_add_u64 v[228:229], v[204:205], 0, s[34:35]
	s_add_i32 m0, s1, 0xc000
	ds_read_b128 v[180:183], v147
	ds_read_b128 v[184:187], v147 offset:1024
	ds_read_b128 v[188:191], v147 offset:2048
	ds_read_b128 v[192:195], v147 offset:3072
	ds_read_b128 v[196:199], v147 offset:4096
	ds_read_b128 v[200:203], v147 offset:5120
	ds_read_b128 v[222:225], v147 offset:6144
	ds_read_b128 v[232:235], v147 offset:7168
	global_load_lds_dwordx4 v[228:229], off
	v_lshl_add_u64 v[210:211], v[138:139], 0, s[10:11]
	s_add_i32 m0, s1, 0xe000
	v_lshl_add_u64 v[152:153], v[210:211], 0, s[34:35]
	global_load_lds_dwordx4 v[152:153], off
	s_waitcnt lgkmcnt(8)
	s_barrier
	s_waitcnt lgkmcnt(0)
	v_mfma_f32_16x16x32_bf16 v[126:129], v[164:167], v[180:183], v[126:129]
	v_mfma_f32_16x16x32_bf16 v[122:125], v[172:175], v[180:183], v[122:125]
	v_mfma_f32_16x16x32_bf16 v[118:121], v[164:167], v[188:191], v[118:121]
	ds_read_b128 v[236:239], v148 offset:16384
	v_mfma_f32_16x16x32_bf16 v[114:117], v[172:175], v[188:191], v[114:117]
	v_mfma_f32_16x16x32_bf16 v[110:113], v[164:167], v[196:199], v[110:113]
	v_mfma_f32_16x16x32_bf16 v[106:109], v[172:175], v[196:199], v[106:109]
	ds_read_b128 v[240:243], v148 offset:17408
	v_mfma_f32_16x16x32_bf16 v[102:105], v[164:167], v[222:225], v[102:105]
	v_mfma_f32_16x16x32_bf16 v[98:101], v[172:175], v[222:225], v[98:101]
	v_mfma_f32_16x16x32_bf16 v[126:129], v[168:171], v[184:187], v[126:129]
	ds_read_b128 v[244:247], v148 offset:18432
	v_mfma_f32_16x16x32_bf16 v[122:125], v[176:179], v[184:187], v[122:125]
	v_mfma_f32_16x16x32_bf16 v[118:121], v[168:171], v[192:195], v[118:121]
	v_mfma_f32_16x16x32_bf16 v[114:117], v[176:179], v[192:195], v[114:117]
	ds_read_b128 v[248:251], v148 offset:19456
	v_mfma_f32_16x16x32_bf16 v[110:113], v[168:171], v[200:203], v[110:113]
	v_mfma_f32_16x16x32_bf16 v[106:109], v[176:179], v[200:203], v[106:109]
	v_mfma_f32_16x16x32_bf16 v[102:105], v[168:171], v[232:235], v[102:105]
	v_mfma_f32_16x16x32_bf16 v[98:101], v[176:179], v[232:235], v[98:101]
	s_barrier
	v_lshl_add_u64 v[216:217], v[132:133], 0, s[10:11]
	s_add_i32 m0, s1, 0xff00
	global_load_lds_dwordx4 v[216:217], off offset:256
	s_add_i32 m0, s1, 0x11f00
	v_lshl_add_u64 v[218:219], v[134:135], 0, s[10:11]
	global_load_lds_dwordx4 v[218:219], off offset:256
	s_barrier
	s_waitcnt lgkmcnt(0)
	v_mfma_f32_16x16x32_bf16 v[94:97], v[236:239], v[180:183], v[94:97]
	v_mfma_f32_16x16x32_bf16 v[90:93], v[244:247], v[180:183], v[90:93]
	v_mfma_f32_16x16x32_bf16 v[86:89], v[236:239], v[188:191], v[86:89]
	v_mfma_f32_16x16x32_bf16 v[82:85], v[244:247], v[188:191], v[82:85]
	v_mfma_f32_16x16x32_bf16 v[78:81], v[236:239], v[196:199], v[78:81]
	v_mfma_f32_16x16x32_bf16 v[74:77], v[244:247], v[196:199], v[74:77]
	v_mfma_f32_16x16x32_bf16 v[70:73], v[236:239], v[222:225], v[70:73]
	v_mfma_f32_16x16x32_bf16 v[66:69], v[244:247], v[222:225], v[66:69]
	v_mfma_f32_16x16x32_bf16 v[94:97], v[240:243], v[184:187], v[94:97]
	v_mfma_f32_16x16x32_bf16 v[90:93], v[248:251], v[184:187], v[90:93]
	v_mfma_f32_16x16x32_bf16 v[86:89], v[240:243], v[192:195], v[86:89]
	v_mfma_f32_16x16x32_bf16 v[82:85], v[248:251], v[192:195], v[82:85]
	v_mfma_f32_16x16x32_bf16 v[78:81], v[240:243], v[200:203], v[78:81]
	v_mfma_f32_16x16x32_bf16 v[74:77], v[248:251], v[200:203], v[74:77]
	v_mfma_f32_16x16x32_bf16 v[70:73], v[240:243], v[232:235], v[70:73]
	v_mfma_f32_16x16x32_bf16 v[66:69], v[248:251], v[232:235], v[66:69]
	v_lshl_add_u64 v[158:159], v[204:205], 0, s[74:75]
	s_mov_b32 m0, s1
	s_barrier
	ds_read_b128 v[180:183], v147 offset:16384
	ds_read_b128 v[184:187], v147 offset:17408
	ds_read_b128 v[188:191], v147 offset:18432
	ds_read_b128 v[192:195], v147 offset:19456
	ds_read_b128 v[196:199], v147 offset:20480
	ds_read_b128 v[200:203], v147 offset:21504
	ds_read_b128 v[222:225], v147 offset:22528
	ds_read_b128 v[232:235], v147 offset:23552
	global_load_lds_dwordx4 v[158:159], off
	s_add_i32 m0, s1, 0x1f00
	s_nop 0
	global_load_lds_dwordx4 v[210:211], off offset:256
	s_barrier
	s_waitcnt lgkmcnt(0)
	v_mfma_f32_16x16x32_bf16 v[62:65], v[164:167], v[180:183], v[62:65]
	v_mfma_f32_16x16x32_bf16 v[58:61], v[172:175], v[180:183], v[58:61]
	v_mfma_f32_16x16x32_bf16 v[54:57], v[164:167], v[188:191], v[54:57]
	v_mfma_f32_16x16x32_bf16 v[50:53], v[172:175], v[188:191], v[50:53]
	v_mfma_f32_16x16x32_bf16 v[46:49], v[164:167], v[196:199], v[46:49]
	v_mfma_f32_16x16x32_bf16 v[42:45], v[172:175], v[196:199], v[42:45]
	v_mfma_f32_16x16x32_bf16 v[38:41], v[164:167], v[222:225], v[38:41]
	v_mfma_f32_16x16x32_bf16 v[34:37], v[172:175], v[222:225], v[34:37]
	v_mfma_f32_16x16x32_bf16 v[62:65], v[168:171], v[184:187], v[62:65]
	v_mfma_f32_16x16x32_bf16 v[58:61], v[176:179], v[184:187], v[58:61]
	v_mfma_f32_16x16x32_bf16 v[54:57], v[168:171], v[192:195], v[54:57]
	v_mfma_f32_16x16x32_bf16 v[50:53], v[176:179], v[192:195], v[50:53]
	v_mfma_f32_16x16x32_bf16 v[46:49], v[168:171], v[200:203], v[46:49]
	v_mfma_f32_16x16x32_bf16 v[42:45], v[176:179], v[200:203], v[42:45]
	v_mfma_f32_16x16x32_bf16 v[38:41], v[168:171], v[232:235], v[38:41]
	v_mfma_f32_16x16x32_bf16 v[34:37], v[176:179], v[232:235], v[34:37]
	s_barrier
	s_add_i32 m0, s1, 0x14000
	v_lshl_add_u64 v[154:155], v[216:217], 0, s[78:79]
	global_load_lds_dwordx4 v[154:155], off
	s_add_i32 m0, s1, 0x16000
	v_lshl_add_u64 v[156:157], v[218:219], 0, s[78:79]
	global_load_lds_dwordx4 v[156:157], off
	s_waitcnt vmcnt(6)
	s_barrier
	v_mfma_f32_16x16x32_bf16 v[30:33], v[236:239], v[180:183], v[30:33]
	v_mfma_f32_16x16x32_bf16 v[26:29], v[244:247], v[180:183], v[26:29]
	v_mfma_f32_16x16x32_bf16 v[22:25], v[236:239], v[188:191], v[22:25]
	ds_read_b128 v[164:167], v148 offset:32768
	v_mfma_f32_16x16x32_bf16 v[18:21], v[244:247], v[188:191], v[18:21]
	v_mfma_f32_16x16x32_bf16 v[14:17], v[236:239], v[196:199], v[14:17]
	v_mfma_f32_16x16x32_bf16 v[10:13], v[244:247], v[196:199], v[10:13]
	ds_read_b128 v[168:171], v148 offset:33792
	v_mfma_f32_16x16x32_bf16 v[6:9], v[236:239], v[222:225], v[6:9]
	v_mfma_f32_16x16x32_bf16 v[2:5], v[244:247], v[222:225], v[2:5]
	v_mfma_f32_16x16x32_bf16 v[30:33], v[240:243], v[184:187], v[30:33]
	ds_read_b128 v[172:175], v148 offset:34816
	v_mfma_f32_16x16x32_bf16 v[26:29], v[248:251], v[184:187], v[26:29]
	v_mfma_f32_16x16x32_bf16 v[22:25], v[240:243], v[192:195], v[22:25]
	v_mfma_f32_16x16x32_bf16 v[18:21], v[248:251], v[192:195], v[18:21]
	ds_read_b128 v[176:179], v148 offset:35840
	v_mfma_f32_16x16x32_bf16 v[14:17], v[240:243], v[200:203], v[14:17]
	v_mfma_f32_16x16x32_bf16 v[10:13], v[248:251], v[200:203], v[10:13]
	v_mfma_f32_16x16x32_bf16 v[6:9], v[240:243], v[232:235], v[6:9]
	v_mfma_f32_16x16x32_bf16 v[2:5], v[248:251], v[232:235], v[2:5]
	s_barrier
	s_add_i32 m0, s1, 0x3f80
	ds_read_b128 v[180:183], v147 offset:32768
	ds_read_b128 v[184:187], v147 offset:33792
	ds_read_b128 v[188:191], v147 offset:34816
	ds_read_b128 v[192:195], v147 offset:35840
	ds_read_b128 v[196:199], v147 offset:36864
	ds_read_b128 v[200:203], v147 offset:37888
	ds_read_b128 v[222:225], v147 offset:38912
	ds_read_b128 v[232:235], v147 offset:39936
	global_load_lds_dwordx4 v[228:229], off offset:128
	s_add_i32 m0, s1, 0x5f80
	s_nop 0
	global_load_lds_dwordx4 v[152:153], off offset:128
	s_waitcnt lgkmcnt(8)
	s_barrier
	s_waitcnt lgkmcnt(0)
	v_mfma_f32_16x16x32_bf16 v[126:129], v[164:167], v[180:183], v[126:129]
	v_mfma_f32_16x16x32_bf16 v[122:125], v[172:175], v[180:183], v[122:125]
	v_mfma_f32_16x16x32_bf16 v[118:121], v[164:167], v[188:191], v[118:121]
	ds_read_b128 v[236:239], v148 offset:49152
	v_mfma_f32_16x16x32_bf16 v[114:117], v[172:175], v[188:191], v[114:117]
	v_mfma_f32_16x16x32_bf16 v[110:113], v[164:167], v[196:199], v[110:113]
	v_mfma_f32_16x16x32_bf16 v[106:109], v[172:175], v[196:199], v[106:109]
	ds_read_b128 v[240:243], v148 offset:50176
	v_mfma_f32_16x16x32_bf16 v[102:105], v[164:167], v[222:225], v[102:105]
	v_mfma_f32_16x16x32_bf16 v[98:101], v[172:175], v[222:225], v[98:101]
	v_mfma_f32_16x16x32_bf16 v[126:129], v[168:171], v[184:187], v[126:129]
	ds_read_b128 v[244:247], v148 offset:51200
	v_mfma_f32_16x16x32_bf16 v[122:125], v[176:179], v[184:187], v[122:125]
	v_mfma_f32_16x16x32_bf16 v[118:121], v[168:171], v[192:195], v[118:121]
	v_mfma_f32_16x16x32_bf16 v[114:117], v[176:179], v[192:195], v[114:117]
	ds_read_b128 v[248:251], v148 offset:52224
	v_mfma_f32_16x16x32_bf16 v[110:113], v[168:171], v[200:203], v[110:113]
	v_mfma_f32_16x16x32_bf16 v[106:109], v[176:179], v[200:203], v[106:109]
	v_mfma_f32_16x16x32_bf16 v[102:105], v[168:171], v[232:235], v[102:105]
	v_mfma_f32_16x16x32_bf16 v[98:101], v[176:179], v[232:235], v[98:101]
	s_barrier
	s_add_i32 m0, s1, 0x17e80
	global_load_lds_dwordx4 v[216:217], off offset:384
	s_add_i32 m0, s1, 0x19e80
	s_nop 0
	global_load_lds_dwordx4 v[218:219], off offset:384
	s_barrier
	s_waitcnt lgkmcnt(0)
	v_mfma_f32_16x16x32_bf16 v[94:97], v[236:239], v[180:183], v[94:97]
	v_mfma_f32_16x16x32_bf16 v[90:93], v[244:247], v[180:183], v[90:93]
	v_mfma_f32_16x16x32_bf16 v[86:89], v[236:239], v[188:191], v[86:89]
	v_mfma_f32_16x16x32_bf16 v[82:85], v[244:247], v[188:191], v[82:85]
	v_mfma_f32_16x16x32_bf16 v[78:81], v[236:239], v[196:199], v[78:81]
	v_mfma_f32_16x16x32_bf16 v[74:77], v[244:247], v[196:199], v[74:77]
	v_mfma_f32_16x16x32_bf16 v[70:73], v[236:239], v[222:225], v[70:73]
	v_mfma_f32_16x16x32_bf16 v[66:69], v[244:247], v[222:225], v[66:69]
	v_mfma_f32_16x16x32_bf16 v[94:97], v[240:243], v[184:187], v[94:97]
	v_mfma_f32_16x16x32_bf16 v[90:93], v[248:251], v[184:187], v[90:93]
	v_mfma_f32_16x16x32_bf16 v[86:89], v[240:243], v[192:195], v[86:89]
	v_mfma_f32_16x16x32_bf16 v[82:85], v[248:251], v[192:195], v[82:85]
	v_mfma_f32_16x16x32_bf16 v[78:81], v[240:243], v[200:203], v[78:81]
	v_mfma_f32_16x16x32_bf16 v[74:77], v[248:251], v[200:203], v[74:77]
	v_mfma_f32_16x16x32_bf16 v[70:73], v[240:243], v[232:235], v[70:73]
	v_mfma_f32_16x16x32_bf16 v[66:69], v[248:251], v[232:235], v[66:69]
	s_add_i32 m0, s1, 0x7e80
	s_barrier
	ds_read_b128 v[180:183], v147 offset:49152
	ds_read_b128 v[184:187], v147 offset:50176
	ds_read_b128 v[188:191], v147 offset:51200
	ds_read_b128 v[192:195], v147 offset:52224
	ds_read_b128 v[196:199], v147 offset:53248
	ds_read_b128 v[200:203], v147 offset:54272
	ds_read_b128 v[222:225], v147 offset:55296
	ds_read_b128 v[232:235], v147 offset:56320
	global_load_lds_dwordx4 v[204:205], off offset:384
	s_add_i32 m0, s1, 0x9e80
	s_nop 0
	global_load_lds_dwordx4 v[210:211], off offset:384
	s_barrier
	s_waitcnt lgkmcnt(0)
	v_mfma_f32_16x16x32_bf16 v[62:65], v[164:167], v[180:183], v[62:65]
	v_mfma_f32_16x16x32_bf16 v[58:61], v[172:175], v[180:183], v[58:61]
	v_mfma_f32_16x16x32_bf16 v[54:57], v[164:167], v[188:191], v[54:57]
	v_mfma_f32_16x16x32_bf16 v[50:53], v[172:175], v[188:191], v[50:53]
	v_mfma_f32_16x16x32_bf16 v[46:49], v[164:167], v[196:199], v[46:49]
	v_mfma_f32_16x16x32_bf16 v[42:45], v[172:175], v[196:199], v[42:45]
	v_mfma_f32_16x16x32_bf16 v[38:41], v[164:167], v[222:225], v[38:41]
	v_mfma_f32_16x16x32_bf16 v[34:37], v[172:175], v[222:225], v[34:37]
	v_mfma_f32_16x16x32_bf16 v[62:65], v[168:171], v[184:187], v[62:65]
	v_mfma_f32_16x16x32_bf16 v[58:61], v[176:179], v[184:187], v[58:61]
	v_mfma_f32_16x16x32_bf16 v[54:57], v[168:171], v[192:195], v[54:57]
	v_mfma_f32_16x16x32_bf16 v[50:53], v[176:179], v[192:195], v[50:53]
	v_mfma_f32_16x16x32_bf16 v[46:49], v[168:171], v[200:203], v[46:49]
	v_mfma_f32_16x16x32_bf16 v[42:45], v[176:179], v[200:203], v[42:45]
	v_mfma_f32_16x16x32_bf16 v[38:41], v[168:171], v[232:235], v[38:41]
	v_mfma_f32_16x16x32_bf16 v[34:37], v[176:179], v[232:235], v[34:37]
	s_barrier
	s_add_i32 m0, s1, 0x1bf80
	s_nop 0
	global_load_lds_dwordx4 v[154:155], off offset:128
	s_add_i32 m0, s1, 0x1df80
	s_nop 0
	global_load_lds_dwordx4 v[156:157], off offset:128
	s_waitcnt vmcnt(6)
	s_barrier
	v_mfma_f32_16x16x32_bf16 v[30:33], v[236:239], v[180:183], v[30:33]
	v_mfma_f32_16x16x32_bf16 v[26:29], v[244:247], v[180:183], v[26:29]
	v_mfma_f32_16x16x32_bf16 v[22:25], v[236:239], v[188:191], v[22:25]
	v_mfma_f32_16x16x32_bf16 v[18:21], v[244:247], v[188:191], v[18:21]
	v_mfma_f32_16x16x32_bf16 v[14:17], v[236:239], v[196:199], v[14:17]
	v_mfma_f32_16x16x32_bf16 v[10:13], v[244:247], v[196:199], v[10:13]
	v_mfma_f32_16x16x32_bf16 v[6:9], v[236:239], v[222:225], v[6:9]
	v_mfma_f32_16x16x32_bf16 v[2:5], v[244:247], v[222:225], v[2:5]
	v_mfma_f32_16x16x32_bf16 v[30:33], v[240:243], v[184:187], v[30:33]
	v_mfma_f32_16x16x32_bf16 v[26:29], v[248:251], v[184:187], v[26:29]
	v_mfma_f32_16x16x32_bf16 v[22:25], v[240:243], v[192:195], v[22:25]
	v_mfma_f32_16x16x32_bf16 v[18:21], v[248:251], v[192:195], v[18:21]
	v_mfma_f32_16x16x32_bf16 v[14:17], v[240:243], v[200:203], v[14:17]
	v_mfma_f32_16x16x32_bf16 v[10:13], v[248:251], v[200:203], v[10:13]
	v_mfma_f32_16x16x32_bf16 v[6:9], v[240:243], v[232:235], v[6:9]
	v_mfma_f32_16x16x32_bf16 v[2:5], v[248:251], v[232:235], v[2:5]
	s_add_i32 s0, s0, 2
	s_add_u32 s10, s10, 0x100
	s_addc_u32 s11, s11, 0
	s_cmpk_lt_u32 s0, 0x54
	s_barrier
	s_cbranch_scc1 .LBB0_761
	s_add_i32 s1, s1, 0x1e000
	s_add_u32 s0, s8, 0x162b80
	s_addc_u32 s1, s9, 0
	v_readfirstlane_b32 s8, v161
	v_lshl_add_u64 v[158:159], s[0:1], 0, v[0:1]
	s_mov_b32 m0, s8
	v_lshl_add_u64 v[130:131], s[0:1], 0, v[130:131]
	v_readfirstlane_b32 s0, v162
	ds_read_b128 v[132:135], v148
	ds_read_b128 v[136:139], v148 offset:1024
	ds_read_b128 v[150:153], v148 offset:2048
	ds_read_b128 v[154:157], v148 offset:3072
	ds_read_b128 v[164:167], v147
	ds_read_b128 v[168:171], v147 offset:1024
	ds_read_b128 v[172:175], v147 offset:2048
	ds_read_b128 v[176:179], v147 offset:3072
	ds_read_b128 v[180:183], v147 offset:4096
	ds_read_b128 v[184:187], v147 offset:5120
	ds_read_b128 v[188:191], v147 offset:6144
	ds_read_b128 v[192:195], v147 offset:7168
	global_load_lds_dwordx4 v[158:159], off
	s_mov_b32 m0, s0
	s_nop 0
	global_load_lds_dwordx4 v[130:131], off
	s_barrier
	s_waitcnt lgkmcnt(0)
	s_setprio 1
	s_waitcnt lgkmcnt(0)
	v_mfma_f32_16x16x32_bf16 v[122:125], v[150:153], v[164:167], v[122:125]
	v_mfma_f32_16x16x32_bf16 v[118:121], v[132:135], v[172:175], v[118:121]
	v_mfma_f32_16x16x32_bf16 v[114:117], v[150:153], v[172:175], v[114:117]
	v_mfma_f32_16x16x32_bf16 v[102:105], v[132:135], v[188:191], v[102:105]
	v_mfma_f32_16x16x32_bf16 v[98:101], v[150:153], v[188:191], v[98:101]
	v_mfma_f32_16x16x32_bf16 v[126:129], v[132:135], v[164:167], v[126:129]
	v_mfma_f32_16x16x32_bf16 v[122:125], v[154:157], v[168:171], v[122:125]
	v_mfma_f32_16x16x32_bf16 v[118:121], v[136:139], v[176:179], v[118:121]
	v_mfma_f32_16x16x32_bf16 v[114:117], v[154:157], v[176:179], v[114:117]
	v_mfma_f32_16x16x32_bf16 v[110:113], v[132:135], v[180:183], v[110:113]
	v_mfma_f32_16x16x32_bf16 v[106:109], v[150:153], v[180:183], v[106:109]
	v_mfma_f32_16x16x32_bf16 v[102:105], v[136:139], v[192:195], v[102:105]
	v_mfma_f32_16x16x32_bf16 v[98:101], v[154:157], v[192:195], v[98:101]
	v_mfma_f32_16x16x32_bf16 v[126:129], v[136:139], v[168:171], v[126:129]
	v_mfma_f32_16x16x32_bf16 v[158:161], v[136:139], v[184:187], v[110:113]
	v_mfma_f32_16x16x32_bf16 v[196:199], v[154:157], v[184:187], v[106:109]
	s_setprio 0
	s_barrier
	ds_read_b128 v[106:109], v148 offset:16384
	ds_read_b128 v[110:113], v148 offset:17408
	ds_read_b128 v[200:203], v148 offset:18432
	ds_read_b128 v[222:225], v148 offset:19456
	s_barrier
	s_waitcnt lgkmcnt(0)
	s_setprio 1
	s_waitcnt lgkmcnt(3)
	v_mfma_f32_16x16x32_bf16 v[86:89], v[106:109], v[172:175], v[86:89]
	s_waitcnt lgkmcnt(1)
	v_mfma_f32_16x16x32_bf16 v[82:85], v[200:203], v[172:175], v[82:85]
	v_mfma_f32_16x16x32_bf16 v[70:73], v[106:109], v[188:191], v[70:73]
	v_mfma_f32_16x16x32_bf16 v[66:69], v[200:203], v[188:191], v[66:69]
	v_mfma_f32_16x16x32_bf16 v[94:97], v[106:109], v[164:167], v[94:97]
	v_mfma_f32_16x16x32_bf16 v[90:93], v[200:203], v[164:167], v[90:93]
	v_mfma_f32_16x16x32_bf16 v[86:89], v[110:113], v[176:179], v[86:89]
	s_waitcnt lgkmcnt(0)
	v_mfma_f32_16x16x32_bf16 v[82:85], v[222:225], v[176:179], v[82:85]
	v_mfma_f32_16x16x32_bf16 v[78:81], v[106:109], v[180:183], v[78:81]
	v_mfma_f32_16x16x32_bf16 v[74:77], v[200:203], v[180:183], v[74:77]
	v_mfma_f32_16x16x32_bf16 v[70:73], v[110:113], v[192:195], v[70:73]
	v_mfma_f32_16x16x32_bf16 v[66:69], v[222:225], v[192:195], v[66:69]
	v_mfma_f32_16x16x32_bf16 v[232:235], v[110:113], v[168:171], v[94:97]
	v_mfma_f32_16x16x32_bf16 v[162:165], v[222:225], v[168:171], v[90:93]
	v_mfma_f32_16x16x32_bf16 v[166:169], v[110:113], v[184:187], v[78:81]
	v_mfma_f32_16x16x32_bf16 v[170:173], v[222:225], v[184:187], v[74:77]
	s_setprio 0
	s_barrier
	s_nop 0
	ds_read_b128 v[74:77], v147 offset:16384
	ds_read_b128 v[78:81], v147 offset:17408
	ds_read_b128 v[90:93], v147 offset:18432
	ds_read_b128 v[94:97], v147 offset:19456
	ds_read_b128 v[174:177], v147 offset:20480
	ds_read_b128 v[178:181], v147 offset:21504
	ds_read_b128 v[182:185], v147 offset:22528
	ds_read_b128 v[186:189], v147 offset:23552
	s_waitcnt vmcnt(4)
	s_barrier
	s_waitcnt lgkmcnt(0)
	s_setprio 1
	s_waitcnt lgkmcnt(7)
	v_mfma_f32_16x16x32_bf16 v[62:65], v[132:135], v[74:77], v[62:65]
	v_mfma_f32_16x16x32_bf16 v[58:61], v[150:153], v[74:77], v[58:61]
	s_waitcnt lgkmcnt(5)
	v_mfma_f32_16x16x32_bf16 v[54:57], v[132:135], v[90:93], v[54:57]
	v_mfma_f32_16x16x32_bf16 v[50:53], v[150:153], v[90:93], v[50:53]
	s_waitcnt lgkmcnt(1)
	v_mfma_f32_16x16x32_bf16 v[38:41], v[132:135], v[182:185], v[38:41]
	v_mfma_f32_16x16x32_bf16 v[34:37], v[150:153], v[182:185], v[34:37]
	v_mfma_f32_16x16x32_bf16 v[62:65], v[136:139], v[78:81], v[62:65]
	v_mfma_f32_16x16x32_bf16 v[58:61], v[154:157], v[78:81], v[58:61]
	v_mfma_f32_16x16x32_bf16 v[54:57], v[136:139], v[94:97], v[54:57]
	v_mfma_f32_16x16x32_bf16 v[50:53], v[154:157], v[94:97], v[50:53]
	v_mfma_f32_16x16x32_bf16 v[46:49], v[132:135], v[174:177], v[46:49]
	v_mfma_f32_16x16x32_bf16 v[42:45], v[150:153], v[174:177], v[42:45]
	s_waitcnt lgkmcnt(0)
	v_mfma_f32_16x16x32_bf16 v[38:41], v[136:139], v[186:189], v[38:41]
	v_mfma_f32_16x16x32_bf16 v[34:37], v[154:157], v[186:189], v[34:37]
	v_mfma_f32_16x16x32_bf16 v[190:193], v[136:139], v[178:181], v[46:49]
	v_mfma_f32_16x16x32_bf16 v[236:239], v[154:157], v[178:181], v[42:45]
	s_setprio 0
	s_setprio 1
	v_mfma_f32_16x16x32_bf16 v[22:25], v[106:109], v[90:93], v[22:25]
	v_mfma_f32_16x16x32_bf16 v[18:21], v[200:203], v[90:93], v[18:21]
	v_mfma_f32_16x16x32_bf16 v[6:9], v[106:109], v[182:185], v[6:9]
	v_mfma_f32_16x16x32_bf16 v[2:5], v[200:203], v[182:185], v[2:5]
	v_mfma_f32_16x16x32_bf16 v[30:33], v[106:109], v[74:77], v[30:33]
	v_mfma_f32_16x16x32_bf16 v[26:29], v[200:203], v[74:77], v[26:29]
	v_mfma_f32_16x16x32_bf16 v[22:25], v[110:113], v[94:97], v[22:25]
	v_mfma_f32_16x16x32_bf16 v[18:21], v[222:225], v[94:97], v[18:21]
	v_mfma_f32_16x16x32_bf16 v[14:17], v[106:109], v[174:177], v[14:17]
	v_mfma_f32_16x16x32_bf16 v[10:13], v[200:203], v[174:177], v[10:13]
	v_mfma_f32_16x16x32_bf16 v[6:9], v[110:113], v[186:189], v[6:9]
	v_mfma_f32_16x16x32_bf16 v[2:5], v[222:225], v[186:189], v[2:5]
	v_mfma_f32_16x16x32_bf16 v[134:137], v[110:113], v[78:81], v[30:33]
	v_mfma_f32_16x16x32_bf16 v[150:153], v[222:225], v[78:81], v[26:29]
	v_mfma_f32_16x16x32_bf16 v[154:157], v[110:113], v[178:181], v[14:17]
	v_mfma_f32_16x16x32_bf16 v[174:177], v[222:225], v[178:181], v[10:13]
	s_setprio 0
	s_barrier
	s_nop 0
	ds_read_b128 v[10:13], v148 offset:32768
	ds_read_b128 v[14:17], v148 offset:33792
	ds_read_b128 v[178:181], v148 offset:34816
	ds_read_b128 v[182:185], v148 offset:35840
	ds_read_b128 v[26:29], v147 offset:32768
	ds_read_b128 v[30:33], v147 offset:33792
	ds_read_b128 v[42:45], v147 offset:34816
	ds_read_b128 v[46:49], v147 offset:35840
	ds_read_b128 v[186:189], v147 offset:36864
	ds_read_b128 v[200:203], v147 offset:37888
	ds_read_b128 v[222:225], v147 offset:38912
	ds_read_b128 v[240:243], v147 offset:39936
	s_waitcnt vmcnt(2)
	s_barrier
	s_waitcnt lgkmcnt(0)
	s_setprio 1
	s_waitcnt lgkmcnt(7)
	v_mfma_f32_16x16x32_bf16 v[74:77], v[10:13], v[26:29], v[126:129]
	s_waitcnt lgkmcnt(6)
	v_mfma_f32_16x16x32_bf16 v[130:133], v[14:17], v[30:33], v[74:77]
	v_mfma_f32_16x16x32_bf16 v[74:77], v[178:181], v[26:29], v[122:125]
	v_mfma_f32_16x16x32_bf16 v[122:125], v[182:185], v[30:33], v[74:77]
	s_waitcnt lgkmcnt(5)
	v_mfma_f32_16x16x32_bf16 v[74:77], v[10:13], v[42:45], v[118:121]
	s_waitcnt lgkmcnt(4)
	v_mfma_f32_16x16x32_bf16 v[110:113], v[14:17], v[46:49], v[74:77]
	v_mfma_f32_16x16x32_bf16 v[74:77], v[178:181], v[42:45], v[114:117]
	v_mfma_f32_16x16x32_bf16 v[106:109], v[182:185], v[46:49], v[74:77]
	s_waitcnt lgkmcnt(3)
	v_mfma_f32_16x16x32_bf16 v[74:77], v[10:13], v[186:189], v[158:161]
	s_waitcnt lgkmcnt(2)
	v_mfma_f32_16x16x32_bf16 v[94:97], v[14:17], v[200:203], v[74:77]
	v_mfma_f32_16x16x32_bf16 v[74:77], v[178:181], v[186:189], v[196:199]
	v_mfma_f32_16x16x32_bf16 v[90:93], v[182:185], v[200:203], v[74:77]
	s_waitcnt lgkmcnt(1)
	v_mfma_f32_16x16x32_bf16 v[74:77], v[10:13], v[222:225], v[102:105]
	s_waitcnt lgkmcnt(0)
	v_mfma_f32_16x16x32_bf16 v[78:81], v[14:17], v[240:243], v[74:77]
	v_mfma_f32_16x16x32_bf16 v[74:77], v[178:181], v[222:225], v[98:101]
	v_mfma_f32_16x16x32_bf16 v[74:77], v[182:185], v[240:243], v[74:77]
	s_setprio 0
	s_barrier
	ds_read_b128 v[126:129], v148 offset:49152
	ds_read_b128 v[158:161], v148 offset:50176
	ds_read_b128 v[194:197], v148 offset:51200
	ds_read_b128 v[244:247], v148 offset:52224
	s_waitcnt vmcnt(0)
	s_barrier
	s_waitcnt lgkmcnt(0)
	s_setprio 1
	s_waitcnt lgkmcnt(3)
	v_mfma_f32_16x16x32_bf16 v[98:101], v[126:129], v[26:29], v[232:235]
	s_waitcnt lgkmcnt(1)
	v_mfma_f32_16x16x32_bf16 v[26:29], v[194:197], v[26:29], v[162:165]
	s_waitcnt lgkmcnt(0)
	v_mfma_f32_16x16x32_bf16 v[114:117], v[244:247], v[30:33], v[26:29]
	v_mfma_f32_16x16x32_bf16 v[26:29], v[126:129], v[42:45], v[86:89]
	v_mfma_f32_16x16x32_bf16 v[102:105], v[158:161], v[46:49], v[26:29]
	v_mfma_f32_16x16x32_bf16 v[26:29], v[194:197], v[42:45], v[82:85]
	v_mfma_f32_16x16x32_bf16 v[118:121], v[158:161], v[30:33], v[98:101]
	v_mfma_f32_16x16x32_bf16 v[98:101], v[244:247], v[46:49], v[26:29]
	v_mfma_f32_16x16x32_bf16 v[26:29], v[126:129], v[186:189], v[166:169]
	v_mfma_f32_16x16x32_bf16 v[86:89], v[158:161], v[200:203], v[26:29]
	v_mfma_f32_16x16x32_bf16 v[26:29], v[194:197], v[186:189], v[170:173]
	v_mfma_f32_16x16x32_bf16 v[82:85], v[244:247], v[200:203], v[26:29]
	v_mfma_f32_16x16x32_bf16 v[26:29], v[126:129], v[222:225], v[70:73]
	v_mfma_f32_16x16x32_bf16 v[70:73], v[158:161], v[240:243], v[26:29]
	v_mfma_f32_16x16x32_bf16 v[26:29], v[194:197], v[222:225], v[66:69]
	v_mfma_f32_16x16x32_bf16 v[66:69], v[244:247], v[240:243], v[26:29]
	s_setprio 0
	s_barrier
	ds_read_b128 v[162:165], v147 offset:49152
	ds_read_b128 v[166:169], v147 offset:50176
	ds_read_b128 v[170:173], v147 offset:51200
	ds_read_b128 v[186:189], v147 offset:52224
	ds_read_b128 v[198:201], v147 offset:53248
	ds_read_b128 v[202:205], v147 offset:54272
	ds_read_b128 v[222:225], v147 offset:55296
	ds_read_b128 v[146:149], v147 offset:56320
	s_barrier
	s_waitcnt lgkmcnt(0)
	s_setprio 1
	s_waitcnt lgkmcnt(7)
	v_mfma_f32_16x16x32_bf16 v[26:29], v[10:13], v[162:165], v[62:65]
	s_waitcnt lgkmcnt(6)
	v_mfma_f32_16x16x32_bf16 v[62:65], v[14:17], v[166:169], v[26:29]
	v_mfma_f32_16x16x32_bf16 v[26:29], v[178:181], v[162:165], v[58:61]
	v_mfma_f32_16x16x32_bf16 v[58:61], v[182:185], v[166:169], v[26:29]
	s_waitcnt lgkmcnt(5)
	v_mfma_f32_16x16x32_bf16 v[26:29], v[10:13], v[170:173], v[54:57]
	s_waitcnt lgkmcnt(4)
	v_mfma_f32_16x16x32_bf16 v[46:49], v[14:17], v[186:189], v[26:29]
	v_mfma_f32_16x16x32_bf16 v[26:29], v[178:181], v[170:173], v[50:53]
	v_mfma_f32_16x16x32_bf16 v[42:45], v[182:185], v[186:189], v[26:29]
	s_waitcnt lgkmcnt(3)
	v_mfma_f32_16x16x32_bf16 v[26:29], v[10:13], v[198:201], v[190:193]
	s_waitcnt lgkmcnt(1)
	v_mfma_f32_16x16x32_bf16 v[10:13], v[10:13], v[222:225], v[38:41]
	v_mfma_f32_16x16x32_bf16 v[30:33], v[14:17], v[202:205], v[26:29]
	v_mfma_f32_16x16x32_bf16 v[26:29], v[178:181], v[198:201], v[236:239]
	s_waitcnt lgkmcnt(0)
	v_mfma_f32_16x16x32_bf16 v[14:17], v[14:17], v[146:149], v[10:13]
	v_mfma_f32_16x16x32_bf16 v[10:13], v[178:181], v[222:225], v[34:37]
	v_mfma_f32_16x16x32_bf16 v[26:29], v[182:185], v[202:205], v[26:29]
	v_mfma_f32_16x16x32_bf16 v[10:13], v[182:185], v[146:149], v[10:13]
	s_setprio 0
	s_setprio 1
	v_mfma_f32_16x16x32_bf16 v[34:37], v[126:129], v[162:165], v[134:137]
	v_mfma_f32_16x16x32_bf16 v[54:57], v[158:161], v[166:169], v[34:37]
	v_mfma_f32_16x16x32_bf16 v[34:37], v[194:197], v[162:165], v[150:153]
	v_mfma_f32_16x16x32_bf16 v[18:21], v[194:197], v[170:173], v[18:21]
	v_mfma_f32_16x16x32_bf16 v[50:53], v[244:247], v[166:169], v[34:37]
	v_mfma_f32_16x16x32_bf16 v[22:25], v[126:129], v[170:173], v[22:25]
	v_mfma_f32_16x16x32_bf16 v[34:37], v[244:247], v[186:189], v[18:21]
	v_mfma_f32_16x16x32_bf16 v[18:21], v[126:129], v[198:201], v[154:157]
	v_mfma_f32_16x16x32_bf16 v[38:41], v[158:161], v[186:189], v[22:25]
	v_mfma_f32_16x16x32_bf16 v[22:25], v[158:161], v[202:205], v[18:21]
	v_mfma_f32_16x16x32_bf16 v[18:21], v[194:197], v[198:201], v[174:177]
	v_mfma_f32_16x16x32_bf16 v[6:9], v[126:129], v[222:225], v[6:9]
	v_mfma_f32_16x16x32_bf16 v[2:5], v[194:197], v[222:225], v[2:5]
	v_mfma_f32_16x16x32_bf16 v[18:21], v[244:247], v[202:205], v[18:21]
	v_mfma_f32_16x16x32_bf16 v[6:9], v[158:161], v[146:149], v[6:9]
	v_mfma_f32_16x16x32_bf16 v[2:5], v[244:247], v[146:149], v[2:5]
	s_setprio 0
	s_movk_i32 s0, 0x100
	v_cmp_gt_u32_e32 vcc, s0, v140
	s_barrier
	s_and_saveexec_b64 s[0:1], vcc
	s_cbranch_execz .LBB0_764
	s_barrier
